# v6
# speedup vs baseline: 1.0289x; 1.0094x over previous
; __device__ __forceinline__ float bf2f(u16 h) { return __uint_as_float(((uint32_t)h) << 16); }
; __device__ __forceinline__ float siluf(float x) { return x * __builtin_amdgcn_rcpf(1.f + __builtin_amdgcn_exp2f(x * -1.4426950408889634f)); }
; __device__ __forceinline__ void ssd_phase(const Params& p, int j, char* smem) {
;     ...
;       {
;         u16* colp = tid_c < 256 ? XR + tid_c : (tid_c < 384 ? Bs + (tid_c - 256) : Cs + (tid_c - 384));
;         const int cld = tid_c < 256 ? XR_LD : CS_LD;
;         const float nh2 = bf2f(colp[(CL - 1) * cld]), nh1 = bf2f(colp[(CL - 2) * cld]), nh0 = bf2f(colp[(CL - 3) * cld]);
;         float a = bf2f(colp[63 * cld]), b1 = bf2f(colp[62 * cld]), c1 = bf2f(colp[61 * cld]);
; #pragma unroll 8
;         for (int s = 63; s >= 3; --s) {
;           const float d = bf2f(colp[(s - 3) * cld]);
;           float o = siluf(cbias + cw3 * a + cw2 * b1 + cw1 * c1 + cw0 * d);
;           if (s >= CL) o = 0.f;
;           colp[s * cld] = f2bf(o);
;           a = b1; b1 = c1; c1 = d;
;         }
.LBB0_248:
	s_or_saveexec_b64 s[4:5], s[4:5]
	v_mov_b32_e32 v113, 0x88
	s_xor_b64 exec, exec, s[4:5]
	v_lshl_add_u32 v102, v207, 1, 0
	v_add_u32_e32 v112, 0x8800, v102
	v_mov_b32_e32 v113, 0x108
	s_or_b64 exec, exec, s[4:5]
	v_mul_i32_i24_e32 v102, s7, v113
	s_movk_i32 s0, 0x7e
	v_lshl_add_u32 v103, v102, 1, v112
	v_sub_u32_e32 v102, v102, v113
	v_mad_u32_u24 v105, v113, s0, v112
	s_movk_i32 s0, 0x7c
	v_lshl_add_u32 v104, v102, 1, v112
	v_sub_u32_e32 v102, v102, v113
	v_mad_u32_u24 v106, v113, s0, v112
	s_movk_i32 s0, 0x7a
	v_lshl_add_u32 v102, v102, 1, v112
	v_mad_u32_u24 v107, v113, s0, v112
	ds_read_u16 v105, v105
	ds_read_u16 v107, v107
	ds_read_u16 v106, v106
	ds_read_u16 v204, v103
	ds_read_u16 v205, v104
	ds_read_u16 v203, v102
	v_mul_u32_u24_e32 v102, 3, v113
	v_lshlrev_b32_e32 v103, 1, v102
	s_movk_i32 s0, 0x76
	v_mad_u32_u24 v116, v113, s0, v103
	v_lshlrev_b32_e32 v104, 2, v102
	s_movk_i32 s0, 0x6e
	v_mad_u32_u24 v117, v113, s0, v104
	v_mad_u32_u24 v118, v113, s0, v103
	v_mul_u32_u24_e32 v103, 6, v102
	s_movk_i32 s0, 0x66
	v_mad_u32_u24 v119, v113, s0, v103
	v_mad_u32_u24 v120, v113, s0, v104
	v_lshlrev_b32_e32 v104, 3, v102
	s_movk_i32 s0, 0x5e
	v_mad_u32_u24 v121, v113, s0, v104
	v_mad_u32_u24 v122, v113, s0, v103
	v_mul_u32_u24_e32 v103, 10, v102
	s_movk_i32 s0, 0x56
	v_mad_u32_u24 v123, v113, s0, v103
	v_mad_u32_u24 v124, v113, s0, v104
	v_mul_u32_u24_e32 v104, 12, v102
	s_movk_i32 s0, 0x4e
	v_mad_u32_u24 v125, v113, s0, v104
	v_mad_u32_u24 v126, v113, s0, v103
	v_mul_u32_u24_e32 v102, 14, v102
	s_movk_i32 s0, 0x46
	s_waitcnt lgkmcnt(5)
	v_lshlrev_b32_e32 v109, 16, v105
	s_waitcnt lgkmcnt(3)
	v_lshlrev_b32_e32 v108, 16, v106
	v_lshlrev_b32_e32 v106, 16, v107
	v_mul_u32_u24_e32 v115, 0x76, v113
	v_lshlrev_b32_e32 v114, 4, v113
	v_mad_u32_u24 v127, v113, s0, v102
	v_mad_u32_u24 v128, v113, s0, v104
	v_mul_u32_u24_e32 v129, 0x7e, v113
	v_mul_u32_u24_e32 v130, 0x78, v113
	s_cmp_lg_u32 s27, 64
	s_cbranch_scc1 .Lmy_conv_orig
	v_readfirstlane_b32 s4, v113
	s_cmp_eq_u32 s4, 0x108
	s_cbranch_scc1 .Lmy_conv_x
	v_mov_b32_e32 v130, v109
	v_mov_b32_e32 v129, v108
	v_mov_b32_e32 v128, v106
	ds_read_u16 v127, v112 offset:16320
	ds_read_u16 v126, v112 offset:16048
	ds_read_u16 v125, v112 offset:15776
	ds_read_u16 v124, v112 offset:15504
	ds_read_u16 v123, v112 offset:15232
	ds_read_u16 v122, v112 offset:14960
	ds_read_u16 v121, v112 offset:14688
	ds_read_u16 v120, v112 offset:14416
	s_waitcnt lgkmcnt(0)
	v_lshlrev_b32_e32 v127, 16, v127
	v_lshlrev_b32_e32 v126, 16, v126
	v_lshlrev_b32_e32 v125, 16, v125
	v_lshlrev_b32_e32 v124, 16, v124
	v_lshlrev_b32_e32 v123, 16, v123
	v_lshlrev_b32_e32 v122, 16, v122
	v_lshlrev_b32_e32 v121, 16, v121
	v_lshlrev_b32_e32 v120, 16, v120
	v_mul_f32_e32 v133, v161, v130
	v_add_f32_e32 v102, v153, v133
	v_mul_f32_e32 v133, v160, v129
	v_add_f32_e32 v102, v133, v102
	v_mul_f32_e32 v133, v158, v128
	v_add_f32_e32 v102, v133, v102
	v_mul_f32_e32 v133, v159, v127
	v_add_f32_e32 v102, v102, v133
	v_mul_f32_e32 v106, 0xbfb8aa3b, v102
	v_exp_f32_e32 v106, v106
	v_mul_f32_e32 v133, v161, v129
	v_add_f32_e32 v107, v153, v133
	v_mul_f32_e32 v133, v160, v128
	v_add_f32_e32 v107, v133, v107
	v_mul_f32_e32 v133, v158, v127
	v_add_f32_e32 v107, v133, v107
	v_mul_f32_e32 v133, v159, v126
	v_add_f32_e32 v107, v107, v133
	v_mul_f32_e32 v108, 0xbfb8aa3b, v107
	v_exp_f32_e32 v108, v108
	v_add_f32_e32 v106, 1.0, v106
	v_rcp_f32_e32 v106, v106
	v_mul_f32_e32 v133, v161, v128
	v_add_f32_e32 v131, v153, v133
	v_mul_f32_e32 v133, v160, v127
	v_add_f32_e32 v131, v133, v131
	v_mul_f32_e32 v133, v158, v126
	v_add_f32_e32 v131, v133, v131
	v_mul_f32_e32 v133, v159, v125
	v_add_f32_e32 v131, v131, v133
	v_mul_f32_e32 v132, 0xbfb8aa3b, v131
	v_exp_f32_e32 v132, v132
	v_add_f32_e32 v108, 1.0, v108
	v_rcp_f32_e32 v108, v108
	v_mul_f32_e32 v102, v102, v106
	v_cvt_pk_bf16_f32 v102, v102, v102
	ds_write_b16 v112, v102 offset:17136
	v_mul_f32_e32 v133, v161, v127
	v_add_f32_e32 v102, v153, v133
	v_mul_f32_e32 v133, v160, v126
	v_add_f32_e32 v102, v133, v102
	v_mul_f32_e32 v133, v158, v125
	v_add_f32_e32 v102, v133, v102
	v_mul_f32_e32 v133, v159, v124
	v_add_f32_e32 v102, v102, v133
	v_mul_f32_e32 v106, 0xbfb8aa3b, v102
	v_exp_f32_e32 v106, v106
	v_add_f32_e32 v132, 1.0, v132
	v_rcp_f32_e32 v132, v132
	v_mul_f32_e32 v107, v107, v108
	v_cvt_pk_bf16_f32 v107, v107, v107
	ds_write_b16 v112, v107 offset:16864
	ds_read_u16 v119, v112 offset:14144
	ds_read_u16 v118, v112 offset:13872
	ds_read_u16 v117, v112 offset:13600
	ds_read_u16 v116, v112 offset:13328
	ds_read_u16 v115, v112 offset:13056
	ds_read_u16 v130, v112 offset:12784
	ds_read_u16 v129, v112 offset:12512
	ds_read_u16 v128, v112 offset:12240
	v_mul_f32_e32 v133, v161, v126
	v_add_f32_e32 v107, v153, v133
	v_mul_f32_e32 v133, v160, v125
	v_add_f32_e32 v107, v133, v107
	v_mul_f32_e32 v133, v158, v124
	v_add_f32_e32 v107, v133, v107
	v_mul_f32_e32 v133, v159, v123
	v_add_f32_e32 v107, v107, v133
	v_mul_f32_e32 v108, 0xbfb8aa3b, v107
	v_exp_f32_e32 v108, v108
	v_add_f32_e32 v106, 1.0, v106
	v_rcp_f32_e32 v106, v106
	v_mul_f32_e32 v131, v131, v132
	v_cvt_pk_bf16_f32 v131, v131, v131
	ds_write_b16 v112, v131 offset:16592
	v_mul_f32_e32 v133, v161, v125
	v_add_f32_e32 v131, v153, v133
	v_mul_f32_e32 v133, v160, v124
	v_add_f32_e32 v131, v133, v131
	v_mul_f32_e32 v133, v158, v123
	v_add_f32_e32 v131, v133, v131
	v_mul_f32_e32 v133, v159, v122
	v_add_f32_e32 v131, v131, v133
	v_mul_f32_e32 v132, 0xbfb8aa3b, v131
	v_exp_f32_e32 v132, v132
	v_add_f32_e32 v108, 1.0, v108
	v_rcp_f32_e32 v108, v108
	v_mul_f32_e32 v102, v102, v106
	v_cvt_pk_bf16_f32 v102, v102, v102
	ds_write_b16 v112, v102 offset:16320
	v_mul_f32_e32 v133, v161, v124
	v_add_f32_e32 v102, v153, v133
	v_mul_f32_e32 v133, v160, v123
	v_add_f32_e32 v102, v133, v102
	v_mul_f32_e32 v133, v158, v122
	v_add_f32_e32 v102, v133, v102
	v_mul_f32_e32 v133, v159, v121
	v_add_f32_e32 v102, v102, v133
	v_mul_f32_e32 v106, 0xbfb8aa3b, v102
	v_exp_f32_e32 v106, v106
	v_add_f32_e32 v132, 1.0, v132
	v_rcp_f32_e32 v132, v132
	v_mul_f32_e32 v107, v107, v108
	v_cvt_pk_bf16_f32 v107, v107, v107
	ds_write_b16 v112, v107 offset:16048
	v_mul_f32_e32 v133, v161, v123
	v_add_f32_e32 v107, v153, v133
	v_mul_f32_e32 v133, v160, v122
	v_add_f32_e32 v107, v133, v107
	v_mul_f32_e32 v133, v158, v121
	v_add_f32_e32 v107, v133, v107
	v_mul_f32_e32 v133, v159, v120
	v_add_f32_e32 v107, v107, v133
	v_mul_f32_e32 v108, 0xbfb8aa3b, v107
	v_exp_f32_e32 v108, v108
	v_add_f32_e32 v106, 1.0, v106
	v_rcp_f32_e32 v106, v106
	v_mul_f32_e32 v131, v131, v132
	v_cvt_pk_bf16_f32 v131, v131, v131
	ds_write_b16 v112, v131 offset:15776
	s_waitcnt lgkmcnt(0)
; __device__ __forceinline__ float bf2f(u16 h) { return __uint_as_float(((uint32_t)h) << 16); }
; __device__ __forceinline__ float siluf(float x) { return x * __builtin_amdgcn_rcpf(1.f + __builtin_amdgcn_exp2f(x * -1.4426950408889634f)); }
; __device__ __forceinline__ void ssd_phase(const Params& p, int j, char* smem) {
;     ...
;         const float nh2 = bf2f(colp[(CL - 1) * cld]), nh1 = bf2f(colp[(CL - 2) * cld]), nh0 = bf2f(colp[(CL - 3) * cld]);
;         float a = bf2f(colp[63 * cld]), b1 = bf2f(colp[62 * cld]), c1 = bf2f(colp[61 * cld]);
; #pragma unroll 8
;         for (int s = 63; s >= 3; --s) {
;           const float d = bf2f(colp[(s - 3) * cld]);
;           float o = siluf(cbias + cw3 * a + cw2 * b1 + cw1 * c1 + cw0 * d);
;           if (s >= CL) o = 0.f;
;           colp[s * cld] = f2bf(o);
;           a = b1; b1 = c1; c1 = d;
;         }
	v_lshlrev_b32_e32 v119, 16, v119
	v_lshlrev_b32_e32 v118, 16, v118
	v_lshlrev_b32_e32 v117, 16, v117
	v_lshlrev_b32_e32 v116, 16, v116
	v_lshlrev_b32_e32 v115, 16, v115
	v_lshlrev_b32_e32 v130, 16, v130
	v_lshlrev_b32_e32 v129, 16, v129
	v_lshlrev_b32_e32 v128, 16, v128
	v_mul_f32_e32 v133, v161, v122
	v_add_f32_e32 v131, v153, v133
	v_mul_f32_e32 v133, v160, v121
	v_add_f32_e32 v131, v133, v131
	v_mul_f32_e32 v133, v158, v120
	v_add_f32_e32 v131, v133, v131
	v_mul_f32_e32 v133, v159, v119
	v_add_f32_e32 v131, v131, v133
	v_mul_f32_e32 v132, 0xbfb8aa3b, v131
	v_exp_f32_e32 v132, v132
	v_add_f32_e32 v108, 1.0, v108
	v_rcp_f32_e32 v108, v108
	v_mul_f32_e32 v102, v102, v106
	v_cvt_pk_bf16_f32 v102, v102, v102
	ds_write_b16 v112, v102 offset:15504
	v_mul_f32_e32 v133, v161, v121
	v_add_f32_e32 v102, v153, v133
	v_mul_f32_e32 v133, v160, v120
	v_add_f32_e32 v102, v133, v102
	v_mul_f32_e32 v133, v158, v119
	v_add_f32_e32 v102, v133, v102
	v_mul_f32_e32 v133, v159, v118
	v_add_f32_e32 v102, v102, v133
	v_mul_f32_e32 v106, 0xbfb8aa3b, v102
	v_exp_f32_e32 v106, v106
	v_add_f32_e32 v132, 1.0, v132
	v_rcp_f32_e32 v132, v132
	v_mul_f32_e32 v107, v107, v108
	v_cvt_pk_bf16_f32 v107, v107, v107
	ds_write_b16 v112, v107 offset:15232
	v_mul_f32_e32 v133, v161, v120
	v_add_f32_e32 v107, v153, v133
	v_mul_f32_e32 v133, v160, v119
	v_add_f32_e32 v107, v133, v107
	v_mul_f32_e32 v133, v158, v118
	v_add_f32_e32 v107, v133, v107
	v_mul_f32_e32 v133, v159, v117
	v_add_f32_e32 v107, v107, v133
	v_mul_f32_e32 v108, 0xbfb8aa3b, v107
	v_exp_f32_e32 v108, v108
	v_add_f32_e32 v106, 1.0, v106
	v_rcp_f32_e32 v106, v106
	v_mul_f32_e32 v131, v131, v132
	v_cvt_pk_bf16_f32 v131, v131, v131
	ds_write_b16 v112, v131 offset:14960
	v_mul_f32_e32 v133, v161, v119
	v_add_f32_e32 v131, v153, v133
	v_mul_f32_e32 v133, v160, v118
	v_add_f32_e32 v131, v133, v131
	v_mul_f32_e32 v133, v158, v117
	v_add_f32_e32 v131, v133, v131
	v_mul_f32_e32 v133, v159, v116
	v_add_f32_e32 v131, v131, v133
	v_mul_f32_e32 v132, 0xbfb8aa3b, v131
	v_exp_f32_e32 v132, v132
	v_add_f32_e32 v108, 1.0, v108
	v_rcp_f32_e32 v108, v108
	v_mul_f32_e32 v102, v102, v106
	v_cvt_pk_bf16_f32 v102, v102, v102
	ds_write_b16 v112, v102 offset:14688
	ds_read_u16 v127, v112 offset:11968
	ds_read_u16 v126, v112 offset:11696
	ds_read_u16 v125, v112 offset:11424
	ds_read_u16 v124, v112 offset:11152
	ds_read_u16 v123, v112 offset:10880
	ds_read_u16 v122, v112 offset:10608
	ds_read_u16 v121, v112 offset:10336
	ds_read_u16 v120, v112 offset:10064
	v_mul_f32_e32 v133, v161, v118
	v_add_f32_e32 v102, v153, v133
	v_mul_f32_e32 v133, v160, v117
	v_add_f32_e32 v102, v133, v102
	v_mul_f32_e32 v133, v158, v116
	v_add_f32_e32 v102, v133, v102
	v_mul_f32_e32 v133, v159, v115
	v_add_f32_e32 v102, v102, v133
	v_mul_f32_e32 v106, 0xbfb8aa3b, v102
	v_exp_f32_e32 v106, v106
	v_add_f32_e32 v132, 1.0, v132
	v_rcp_f32_e32 v132, v132
	v_mul_f32_e32 v107, v107, v108
	v_cvt_pk_bf16_f32 v107, v107, v107
	ds_write_b16 v112, v107 offset:14416
	v_mul_f32_e32 v133, v161, v117
	v_add_f32_e32 v107, v153, v133
	v_mul_f32_e32 v133, v160, v116
	v_add_f32_e32 v107, v133, v107
	v_mul_f32_e32 v133, v158, v115
	v_add_f32_e32 v107, v133, v107
	v_mul_f32_e32 v133, v159, v130
	v_add_f32_e32 v107, v107, v133
	v_mul_f32_e32 v108, 0xbfb8aa3b, v107
	v_exp_f32_e32 v108, v108
	v_add_f32_e32 v106, 1.0, v106
	v_rcp_f32_e32 v106, v106
	v_mul_f32_e32 v131, v131, v132
	v_cvt_pk_bf16_f32 v131, v131, v131
	ds_write_b16 v112, v131 offset:14144
	v_mul_f32_e32 v133, v161, v116
	v_add_f32_e32 v131, v153, v133
	v_mul_f32_e32 v133, v160, v115
	v_add_f32_e32 v131, v133, v131
	v_mul_f32_e32 v133, v158, v130
	v_add_f32_e32 v131, v133, v131
	v_mul_f32_e32 v133, v159, v129
	v_add_f32_e32 v131, v131, v133
	v_mul_f32_e32 v132, 0xbfb8aa3b, v131
	v_exp_f32_e32 v132, v132
	v_add_f32_e32 v108, 1.0, v108
	v_rcp_f32_e32 v108, v108
	v_mul_f32_e32 v102, v102, v106
	v_cvt_pk_bf16_f32 v102, v102, v102
	ds_write_b16 v112, v102 offset:13872
	v_mul_f32_e32 v133, v161, v115
	v_add_f32_e32 v102, v153, v133
	v_mul_f32_e32 v133, v160, v130
	v_add_f32_e32 v102, v133, v102
	v_mul_f32_e32 v133, v158, v129
	v_add_f32_e32 v102, v133, v102
	v_mul_f32_e32 v133, v159, v128
	v_add_f32_e32 v102, v102, v133
	v_mul_f32_e32 v106, 0xbfb8aa3b, v102
	v_exp_f32_e32 v106, v106
	v_add_f32_e32 v132, 1.0, v132
	v_rcp_f32_e32 v132, v132
	v_mul_f32_e32 v107, v107, v108
	v_cvt_pk_bf16_f32 v107, v107, v107
	ds_write_b16 v112, v107 offset:13600
	s_waitcnt lgkmcnt(0)
; __device__ __forceinline__ float bf2f(u16 h) { return __uint_as_float(((uint32_t)h) << 16); }
; __device__ __forceinline__ float siluf(float x) { return x * __builtin_amdgcn_rcpf(1.f + __builtin_amdgcn_exp2f(x * -1.4426950408889634f)); }
; __device__ __forceinline__ void ssd_phase(const Params& p, int j, char* smem) {
;     ...
;         const float nh2 = bf2f(colp[(CL - 1) * cld]), nh1 = bf2f(colp[(CL - 2) * cld]), nh0 = bf2f(colp[(CL - 3) * cld]);
;         float a = bf2f(colp[63 * cld]), b1 = bf2f(colp[62 * cld]), c1 = bf2f(colp[61 * cld]);
; #pragma unroll 8
;         for (int s = 63; s >= 3; --s) {
;           const float d = bf2f(colp[(s - 3) * cld]);
;           float o = siluf(cbias + cw3 * a + cw2 * b1 + cw1 * c1 + cw0 * d);
;           if (s >= CL) o = 0.f;
;           colp[s * cld] = f2bf(o);
;           a = b1; b1 = c1; c1 = d;
;         }
	v_lshlrev_b32_e32 v127, 16, v127
	v_lshlrev_b32_e32 v126, 16, v126
	v_lshlrev_b32_e32 v125, 16, v125
	v_lshlrev_b32_e32 v124, 16, v124
	v_lshlrev_b32_e32 v123, 16, v123
	v_lshlrev_b32_e32 v122, 16, v122
	v_lshlrev_b32_e32 v121, 16, v121
	v_lshlrev_b32_e32 v120, 16, v120
	v_mul_f32_e32 v133, v161, v130
	v_add_f32_e32 v107, v153, v133
	v_mul_f32_e32 v133, v160, v129
	v_add_f32_e32 v107, v133, v107
	v_mul_f32_e32 v133, v158, v128
	v_add_f32_e32 v107, v133, v107
	v_mul_f32_e32 v133, v159, v127
	v_add_f32_e32 v107, v107, v133
	v_mul_f32_e32 v108, 0xbfb8aa3b, v107
	v_exp_f32_e32 v108, v108
	v_add_f32_e32 v106, 1.0, v106
	v_rcp_f32_e32 v106, v106
	v_mul_f32_e32 v131, v131, v132
	v_cvt_pk_bf16_f32 v131, v131, v131
	ds_write_b16 v112, v131 offset:13328
	v_mul_f32_e32 v133, v161, v129
	v_add_f32_e32 v131, v153, v133
	v_mul_f32_e32 v133, v160, v128
	v_add_f32_e32 v131, v133, v131
	v_mul_f32_e32 v133, v158, v127
	v_add_f32_e32 v131, v133, v131
	v_mul_f32_e32 v133, v159, v126
	v_add_f32_e32 v131, v131, v133
	v_mul_f32_e32 v132, 0xbfb8aa3b, v131
	v_exp_f32_e32 v132, v132
	v_add_f32_e32 v108, 1.0, v108
	v_rcp_f32_e32 v108, v108
	v_mul_f32_e32 v102, v102, v106
	v_cvt_pk_bf16_f32 v102, v102, v102
	ds_write_b16 v112, v102 offset:13056
	v_mul_f32_e32 v133, v161, v128
	v_add_f32_e32 v102, v153, v133
	v_mul_f32_e32 v133, v160, v127
	v_add_f32_e32 v102, v133, v102
	v_mul_f32_e32 v133, v158, v126
	v_add_f32_e32 v102, v133, v102
	v_mul_f32_e32 v133, v159, v125
	v_add_f32_e32 v102, v102, v133
	v_mul_f32_e32 v106, 0xbfb8aa3b, v102
	v_exp_f32_e32 v106, v106
	v_add_f32_e32 v132, 1.0, v132
	v_rcp_f32_e32 v132, v132
	v_mul_f32_e32 v107, v107, v108
	v_cvt_pk_bf16_f32 v107, v107, v107
	ds_write_b16 v112, v107 offset:12784
	v_mul_f32_e32 v133, v161, v127
	v_add_f32_e32 v107, v153, v133
	v_mul_f32_e32 v133, v160, v126
	v_add_f32_e32 v107, v133, v107
	v_mul_f32_e32 v133, v158, v125
	v_add_f32_e32 v107, v133, v107
	v_mul_f32_e32 v133, v159, v124
	v_add_f32_e32 v107, v107, v133
	v_mul_f32_e32 v108, 0xbfb8aa3b, v107
	v_exp_f32_e32 v108, v108
	v_add_f32_e32 v106, 1.0, v106
	v_rcp_f32_e32 v106, v106
	v_mul_f32_e32 v131, v131, v132
	v_cvt_pk_bf16_f32 v131, v131, v131
	ds_write_b16 v112, v131 offset:12512
	ds_read_u16 v119, v112 offset:9792
	ds_read_u16 v118, v112 offset:9520
	ds_read_u16 v117, v112 offset:9248
	ds_read_u16 v116, v112 offset:8976
	ds_read_u16 v115, v112 offset:8704
	ds_read_u16 v130, v112 offset:8432
	ds_read_u16 v129, v112 offset:8160
	ds_read_u16 v128, v112 offset:7888
	v_mul_f32_e32 v133, v161, v126
	v_add_f32_e32 v131, v153, v133
	v_mul_f32_e32 v133, v160, v125
	v_add_f32_e32 v131, v133, v131
	v_mul_f32_e32 v133, v158, v124
	v_add_f32_e32 v131, v133, v131
	v_mul_f32_e32 v133, v159, v123
	v_add_f32_e32 v131, v131, v133
	v_mul_f32_e32 v132, 0xbfb8aa3b, v131
	v_exp_f32_e32 v132, v132
	v_add_f32_e32 v108, 1.0, v108
	v_rcp_f32_e32 v108, v108
	v_mul_f32_e32 v102, v102, v106
	v_cvt_pk_bf16_f32 v102, v102, v102
	ds_write_b16 v112, v102 offset:12240
	v_mul_f32_e32 v133, v161, v125
	v_add_f32_e32 v102, v153, v133
	v_mul_f32_e32 v133, v160, v124
	v_add_f32_e32 v102, v133, v102
	v_mul_f32_e32 v133, v158, v123
	v_add_f32_e32 v102, v133, v102
	v_mul_f32_e32 v133, v159, v122
	v_add_f32_e32 v102, v102, v133
	v_mul_f32_e32 v106, 0xbfb8aa3b, v102
	v_exp_f32_e32 v106, v106
	v_add_f32_e32 v132, 1.0, v132
	v_rcp_f32_e32 v132, v132
	v_mul_f32_e32 v107, v107, v108
	v_cvt_pk_bf16_f32 v107, v107, v107
	ds_write_b16 v112, v107 offset:11968
	v_mul_f32_e32 v133, v161, v124
	v_add_f32_e32 v107, v153, v133
	v_mul_f32_e32 v133, v160, v123
	v_add_f32_e32 v107, v133, v107
	v_mul_f32_e32 v133, v158, v122
	v_add_f32_e32 v107, v133, v107
	v_mul_f32_e32 v133, v159, v121
	v_add_f32_e32 v107, v107, v133
	v_mul_f32_e32 v108, 0xbfb8aa3b, v107
	v_exp_f32_e32 v108, v108
	v_add_f32_e32 v106, 1.0, v106
	v_rcp_f32_e32 v106, v106
	v_mul_f32_e32 v131, v131, v132
	v_cvt_pk_bf16_f32 v131, v131, v131
	ds_write_b16 v112, v131 offset:11696
	v_mul_f32_e32 v133, v161, v123
	v_add_f32_e32 v131, v153, v133
	v_mul_f32_e32 v133, v160, v122
	v_add_f32_e32 v131, v133, v131
	v_mul_f32_e32 v133, v158, v121
	v_add_f32_e32 v131, v133, v131
	v_mul_f32_e32 v133, v159, v120
	v_add_f32_e32 v131, v131, v133
	v_mul_f32_e32 v132, 0xbfb8aa3b, v131
	v_exp_f32_e32 v132, v132
	v_add_f32_e32 v108, 1.0, v108
	v_rcp_f32_e32 v108, v108
	v_mul_f32_e32 v102, v102, v106
	v_cvt_pk_bf16_f32 v102, v102, v102
	ds_write_b16 v112, v102 offset:11424
	s_waitcnt lgkmcnt(0)
; __device__ __forceinline__ float bf2f(u16 h) { return __uint_as_float(((uint32_t)h) << 16); }
; __device__ __forceinline__ float siluf(float x) { return x * __builtin_amdgcn_rcpf(1.f + __builtin_amdgcn_exp2f(x * -1.4426950408889634f)); }
; __device__ __forceinline__ void ssd_phase(const Params& p, int j, char* smem) {
;     ...
;         const float nh2 = bf2f(colp[(CL - 1) * cld]), nh1 = bf2f(colp[(CL - 2) * cld]), nh0 = bf2f(colp[(CL - 3) * cld]);
;         float a = bf2f(colp[63 * cld]), b1 = bf2f(colp[62 * cld]), c1 = bf2f(colp[61 * cld]);
; #pragma unroll 8
;         for (int s = 63; s >= 3; --s) {
;           const float d = bf2f(colp[(s - 3) * cld]);
;           float o = siluf(cbias + cw3 * a + cw2 * b1 + cw1 * c1 + cw0 * d);
;           if (s >= CL) o = 0.f;
;           colp[s * cld] = f2bf(o);
;           a = b1; b1 = c1; c1 = d;
;         }
	v_lshlrev_b32_e32 v119, 16, v119
	v_lshlrev_b32_e32 v118, 16, v118
	v_lshlrev_b32_e32 v117, 16, v117
	v_lshlrev_b32_e32 v116, 16, v116
	v_lshlrev_b32_e32 v115, 16, v115
	v_lshlrev_b32_e32 v130, 16, v130
	v_lshlrev_b32_e32 v129, 16, v129
	v_lshlrev_b32_e32 v128, 16, v128
	v_mul_f32_e32 v133, v161, v122
	v_add_f32_e32 v102, v153, v133
	v_mul_f32_e32 v133, v160, v121
	v_add_f32_e32 v102, v133, v102
	v_mul_f32_e32 v133, v158, v120
	v_add_f32_e32 v102, v133, v102
	v_mul_f32_e32 v133, v159, v119
	v_add_f32_e32 v102, v102, v133
	v_mul_f32_e32 v106, 0xbfb8aa3b, v102
	v_exp_f32_e32 v106, v106
	v_add_f32_e32 v132, 1.0, v132
	v_rcp_f32_e32 v132, v132
	v_mul_f32_e32 v107, v107, v108
	v_cvt_pk_bf16_f32 v107, v107, v107
	ds_write_b16 v112, v107 offset:11152
	v_mul_f32_e32 v133, v161, v121
	v_add_f32_e32 v107, v153, v133
	v_mul_f32_e32 v133, v160, v120
	v_add_f32_e32 v107, v133, v107
	v_mul_f32_e32 v133, v158, v119
	v_add_f32_e32 v107, v133, v107
	v_mul_f32_e32 v133, v159, v118
	v_add_f32_e32 v107, v107, v133
	v_mul_f32_e32 v108, 0xbfb8aa3b, v107
	v_exp_f32_e32 v108, v108
	v_add_f32_e32 v106, 1.0, v106
	v_rcp_f32_e32 v106, v106
	v_mul_f32_e32 v131, v131, v132
	v_cvt_pk_bf16_f32 v131, v131, v131
	ds_write_b16 v112, v131 offset:10880
	v_mul_f32_e32 v133, v161, v120
	v_add_f32_e32 v131, v153, v133
	v_mul_f32_e32 v133, v160, v119
	v_add_f32_e32 v131, v133, v131
	v_mul_f32_e32 v133, v158, v118
	v_add_f32_e32 v131, v133, v131
	v_mul_f32_e32 v133, v159, v117
	v_add_f32_e32 v131, v131, v133
	v_mul_f32_e32 v132, 0xbfb8aa3b, v131
	v_exp_f32_e32 v132, v132
	v_add_f32_e32 v108, 1.0, v108
	v_rcp_f32_e32 v108, v108
	v_mul_f32_e32 v102, v102, v106
	v_cvt_pk_bf16_f32 v102, v102, v102
	ds_write_b16 v112, v102 offset:10608
	v_mul_f32_e32 v133, v161, v119
	v_add_f32_e32 v102, v153, v133
	v_mul_f32_e32 v133, v160, v118
	v_add_f32_e32 v102, v133, v102
	v_mul_f32_e32 v133, v158, v117
	v_add_f32_e32 v102, v133, v102
	v_mul_f32_e32 v133, v159, v116
	v_add_f32_e32 v102, v102, v133
	v_mul_f32_e32 v106, 0xbfb8aa3b, v102
	v_exp_f32_e32 v106, v106
	v_add_f32_e32 v132, 1.0, v132
	v_rcp_f32_e32 v132, v132
	v_mul_f32_e32 v107, v107, v108
	v_cvt_pk_bf16_f32 v107, v107, v107
	ds_write_b16 v112, v107 offset:10336
	ds_read_u16 v127, v112 offset:7616
	ds_read_u16 v126, v112 offset:7344
	ds_read_u16 v125, v112 offset:7072
	ds_read_u16 v124, v112 offset:6800
	ds_read_u16 v123, v112 offset:6528
	ds_read_u16 v122, v112 offset:6256
	ds_read_u16 v121, v112 offset:5984
	ds_read_u16 v120, v112 offset:5712
	v_mul_f32_e32 v133, v161, v118
	v_add_f32_e32 v107, v153, v133
	v_mul_f32_e32 v133, v160, v117
	v_add_f32_e32 v107, v133, v107
	v_mul_f32_e32 v133, v158, v116
	v_add_f32_e32 v107, v133, v107
	v_mul_f32_e32 v133, v159, v115
	v_add_f32_e32 v107, v107, v133
	v_mul_f32_e32 v108, 0xbfb8aa3b, v107
	v_exp_f32_e32 v108, v108
	v_add_f32_e32 v106, 1.0, v106
	v_rcp_f32_e32 v106, v106
	v_mul_f32_e32 v131, v131, v132
	v_cvt_pk_bf16_f32 v131, v131, v131
	ds_write_b16 v112, v131 offset:10064
	v_mul_f32_e32 v133, v161, v117
	v_add_f32_e32 v131, v153, v133
	v_mul_f32_e32 v133, v160, v116
	v_add_f32_e32 v131, v133, v131
	v_mul_f32_e32 v133, v158, v115
	v_add_f32_e32 v131, v133, v131
	v_mul_f32_e32 v133, v159, v130
	v_add_f32_e32 v131, v131, v133
	v_mul_f32_e32 v132, 0xbfb8aa3b, v131
	v_exp_f32_e32 v132, v132
	v_add_f32_e32 v108, 1.0, v108
	v_rcp_f32_e32 v108, v108
	v_mul_f32_e32 v102, v102, v106
	v_cvt_pk_bf16_f32 v102, v102, v102
	ds_write_b16 v112, v102 offset:9792
	v_mul_f32_e32 v133, v161, v116
	v_add_f32_e32 v102, v153, v133
	v_mul_f32_e32 v133, v160, v115
	v_add_f32_e32 v102, v133, v102
	v_mul_f32_e32 v133, v158, v130
	v_add_f32_e32 v102, v133, v102
	v_mul_f32_e32 v133, v159, v129
	v_add_f32_e32 v102, v102, v133
	v_mul_f32_e32 v106, 0xbfb8aa3b, v102
	v_exp_f32_e32 v106, v106
	v_add_f32_e32 v132, 1.0, v132
	v_rcp_f32_e32 v132, v132
	v_mul_f32_e32 v107, v107, v108
	v_cvt_pk_bf16_f32 v107, v107, v107
	ds_write_b16 v112, v107 offset:9520
	v_mul_f32_e32 v133, v161, v115
	v_add_f32_e32 v107, v153, v133
	v_mul_f32_e32 v133, v160, v130
	v_add_f32_e32 v107, v133, v107
	v_mul_f32_e32 v133, v158, v129
	v_add_f32_e32 v107, v133, v107
	v_mul_f32_e32 v133, v159, v128
	v_add_f32_e32 v107, v107, v133
	v_mul_f32_e32 v108, 0xbfb8aa3b, v107
	v_exp_f32_e32 v108, v108
	v_add_f32_e32 v106, 1.0, v106
	v_rcp_f32_e32 v106, v106
	v_mul_f32_e32 v131, v131, v132
	v_cvt_pk_bf16_f32 v131, v131, v131
	ds_write_b16 v112, v131 offset:9248
	s_waitcnt lgkmcnt(0)
; __device__ __forceinline__ float bf2f(u16 h) { return __uint_as_float(((uint32_t)h) << 16); }
; __device__ __forceinline__ float siluf(float x) { return x * __builtin_amdgcn_rcpf(1.f + __builtin_amdgcn_exp2f(x * -1.4426950408889634f)); }
; __device__ __forceinline__ void ssd_phase(const Params& p, int j, char* smem) {
;     ...
;         const float nh2 = bf2f(colp[(CL - 1) * cld]), nh1 = bf2f(colp[(CL - 2) * cld]), nh0 = bf2f(colp[(CL - 3) * cld]);
;         float a = bf2f(colp[63 * cld]), b1 = bf2f(colp[62 * cld]), c1 = bf2f(colp[61 * cld]);
; #pragma unroll 8
;         for (int s = 63; s >= 3; --s) {
;           const float d = bf2f(colp[(s - 3) * cld]);
;           float o = siluf(cbias + cw3 * a + cw2 * b1 + cw1 * c1 + cw0 * d);
;           if (s >= CL) o = 0.f;
;           colp[s * cld] = f2bf(o);
;           a = b1; b1 = c1; c1 = d;
;         }
	v_lshlrev_b32_e32 v127, 16, v127
	v_lshlrev_b32_e32 v126, 16, v126
	v_lshlrev_b32_e32 v125, 16, v125
	v_lshlrev_b32_e32 v124, 16, v124
	v_lshlrev_b32_e32 v123, 16, v123
	v_lshlrev_b32_e32 v122, 16, v122
	v_lshlrev_b32_e32 v121, 16, v121
	v_lshlrev_b32_e32 v120, 16, v120
	v_mul_f32_e32 v133, v161, v130
	v_add_f32_e32 v131, v153, v133
	v_mul_f32_e32 v133, v160, v129
	v_add_f32_e32 v131, v133, v131
	v_mul_f32_e32 v133, v158, v128
	v_add_f32_e32 v131, v133, v131
	v_mul_f32_e32 v133, v159, v127
	v_add_f32_e32 v131, v131, v133
	v_mul_f32_e32 v132, 0xbfb8aa3b, v131
	v_exp_f32_e32 v132, v132
	v_add_f32_e32 v108, 1.0, v108
	v_rcp_f32_e32 v108, v108
	v_mul_f32_e32 v102, v102, v106
	v_cvt_pk_bf16_f32 v102, v102, v102
	ds_write_b16 v112, v102 offset:8976
	v_mul_f32_e32 v133, v161, v129
	v_add_f32_e32 v102, v153, v133
	v_mul_f32_e32 v133, v160, v128
	v_add_f32_e32 v102, v133, v102
	v_mul_f32_e32 v133, v158, v127
	v_add_f32_e32 v102, v133, v102
	v_mul_f32_e32 v133, v159, v126
	v_add_f32_e32 v102, v102, v133
	v_mul_f32_e32 v106, 0xbfb8aa3b, v102
	v_exp_f32_e32 v106, v106
	v_add_f32_e32 v132, 1.0, v132
	v_rcp_f32_e32 v132, v132
	v_mul_f32_e32 v107, v107, v108
	v_cvt_pk_bf16_f32 v107, v107, v107
	ds_write_b16 v112, v107 offset:8704
	v_mul_f32_e32 v133, v161, v128
	v_add_f32_e32 v107, v153, v133
	v_mul_f32_e32 v133, v160, v127
	v_add_f32_e32 v107, v133, v107
	v_mul_f32_e32 v133, v158, v126
	v_add_f32_e32 v107, v133, v107
	v_mul_f32_e32 v133, v159, v125
	v_add_f32_e32 v107, v107, v133
	v_mul_f32_e32 v108, 0xbfb8aa3b, v107
	v_exp_f32_e32 v108, v108
	v_add_f32_e32 v106, 1.0, v106
	v_rcp_f32_e32 v106, v106
	v_mul_f32_e32 v131, v131, v132
	v_cvt_pk_bf16_f32 v131, v131, v131
	ds_write_b16 v112, v131 offset:8432
	v_mul_f32_e32 v133, v161, v127
	v_add_f32_e32 v131, v153, v133
	v_mul_f32_e32 v133, v160, v126
	v_add_f32_e32 v131, v133, v131
	v_mul_f32_e32 v133, v158, v125
	v_add_f32_e32 v131, v133, v131
	v_mul_f32_e32 v133, v159, v124
	v_add_f32_e32 v131, v131, v133
	v_mul_f32_e32 v132, 0xbfb8aa3b, v131
	v_exp_f32_e32 v132, v132
	v_add_f32_e32 v108, 1.0, v108
	v_rcp_f32_e32 v108, v108
	v_mul_f32_e32 v102, v102, v106
	v_cvt_pk_bf16_f32 v102, v102, v102
	ds_write_b16 v112, v102 offset:8160
	ds_read_u16 v119, v112 offset:5440
	ds_read_u16 v118, v112 offset:5168
	ds_read_u16 v117, v112 offset:4896
	ds_read_u16 v116, v112 offset:4624
	ds_read_u16 v115, v112 offset:4352
	ds_read_u16 v130, v112 offset:4080
	ds_read_u16 v129, v112 offset:3808
	ds_read_u16 v128, v112 offset:3536
	v_mul_f32_e32 v133, v161, v126
	v_add_f32_e32 v102, v153, v133
	v_mul_f32_e32 v133, v160, v125
	v_add_f32_e32 v102, v133, v102
	v_mul_f32_e32 v133, v158, v124
	v_add_f32_e32 v102, v133, v102
	v_mul_f32_e32 v133, v159, v123
	v_add_f32_e32 v102, v102, v133
	v_mul_f32_e32 v106, 0xbfb8aa3b, v102
	v_exp_f32_e32 v106, v106
	v_add_f32_e32 v132, 1.0, v132
	v_rcp_f32_e32 v132, v132
	v_mul_f32_e32 v107, v107, v108
	v_cvt_pk_bf16_f32 v107, v107, v107
	ds_write_b16 v112, v107 offset:7888
	v_mul_f32_e32 v133, v161, v125
	v_add_f32_e32 v107, v153, v133
	v_mul_f32_e32 v133, v160, v124
	v_add_f32_e32 v107, v133, v107
	v_mul_f32_e32 v133, v158, v123
	v_add_f32_e32 v107, v133, v107
	v_mul_f32_e32 v133, v159, v122
	v_add_f32_e32 v107, v107, v133
	v_mul_f32_e32 v108, 0xbfb8aa3b, v107
	v_exp_f32_e32 v108, v108
	v_add_f32_e32 v106, 1.0, v106
	v_rcp_f32_e32 v106, v106
	v_mul_f32_e32 v131, v131, v132
	v_cvt_pk_bf16_f32 v131, v131, v131
	ds_write_b16 v112, v131 offset:7616
	v_mul_f32_e32 v133, v161, v124
	v_add_f32_e32 v131, v153, v133
	v_mul_f32_e32 v133, v160, v123
	v_add_f32_e32 v131, v133, v131
	v_mul_f32_e32 v133, v158, v122
	v_add_f32_e32 v131, v133, v131
	v_mul_f32_e32 v133, v159, v121
	v_add_f32_e32 v131, v131, v133
	v_mul_f32_e32 v132, 0xbfb8aa3b, v131
	v_exp_f32_e32 v132, v132
	v_add_f32_e32 v108, 1.0, v108
	v_rcp_f32_e32 v108, v108
	v_mul_f32_e32 v102, v102, v106
	v_cvt_pk_bf16_f32 v102, v102, v102
	ds_write_b16 v112, v102 offset:7344
	v_mul_f32_e32 v133, v161, v123
	v_add_f32_e32 v102, v153, v133
	v_mul_f32_e32 v133, v160, v122
	v_add_f32_e32 v102, v133, v102
	v_mul_f32_e32 v133, v158, v121
	v_add_f32_e32 v102, v133, v102
	v_mul_f32_e32 v133, v159, v120
	v_add_f32_e32 v102, v102, v133
	v_mul_f32_e32 v106, 0xbfb8aa3b, v102
	v_exp_f32_e32 v106, v106
	v_add_f32_e32 v132, 1.0, v132
	v_rcp_f32_e32 v132, v132
	v_mul_f32_e32 v107, v107, v108
	v_cvt_pk_bf16_f32 v107, v107, v107
	ds_write_b16 v112, v107 offset:7072
	s_waitcnt lgkmcnt(0)
; __device__ __forceinline__ float bf2f(u16 h) { return __uint_as_float(((uint32_t)h) << 16); }
; __device__ __forceinline__ float siluf(float x) { return x * __builtin_amdgcn_rcpf(1.f + __builtin_amdgcn_exp2f(x * -1.4426950408889634f)); }
; __device__ __forceinline__ void ssd_phase(const Params& p, int j, char* smem) {
;     ...
;         const float nh2 = bf2f(colp[(CL - 1) * cld]), nh1 = bf2f(colp[(CL - 2) * cld]), nh0 = bf2f(colp[(CL - 3) * cld]);
;         float a = bf2f(colp[63 * cld]), b1 = bf2f(colp[62 * cld]), c1 = bf2f(colp[61 * cld]);
; #pragma unroll 8
;         for (int s = 63; s >= 3; --s) {
;           const float d = bf2f(colp[(s - 3) * cld]);
;           float o = siluf(cbias + cw3 * a + cw2 * b1 + cw1 * c1 + cw0 * d);
;           if (s >= CL) o = 0.f;
;           colp[s * cld] = f2bf(o);
;           a = b1; b1 = c1; c1 = d;
;         }
	v_lshlrev_b32_e32 v119, 16, v119
	v_lshlrev_b32_e32 v118, 16, v118
	v_lshlrev_b32_e32 v117, 16, v117
	v_lshlrev_b32_e32 v116, 16, v116
	v_lshlrev_b32_e32 v115, 16, v115
	v_lshlrev_b32_e32 v130, 16, v130
	v_lshlrev_b32_e32 v129, 16, v129
	v_lshlrev_b32_e32 v128, 16, v128
	v_mul_f32_e32 v133, v161, v122
	v_add_f32_e32 v107, v153, v133
	v_mul_f32_e32 v133, v160, v121
	v_add_f32_e32 v107, v133, v107
	v_mul_f32_e32 v133, v158, v120
	v_add_f32_e32 v107, v133, v107
	v_mul_f32_e32 v133, v159, v119
	v_add_f32_e32 v107, v107, v133
	v_mul_f32_e32 v108, 0xbfb8aa3b, v107
	v_exp_f32_e32 v108, v108
	v_add_f32_e32 v106, 1.0, v106
	v_rcp_f32_e32 v106, v106
	v_mul_f32_e32 v131, v131, v132
	v_cvt_pk_bf16_f32 v131, v131, v131
	ds_write_b16 v112, v131 offset:6800
	v_mul_f32_e32 v133, v161, v121
	v_add_f32_e32 v131, v153, v133
	v_mul_f32_e32 v133, v160, v120
	v_add_f32_e32 v131, v133, v131
	v_mul_f32_e32 v133, v158, v119
	v_add_f32_e32 v131, v133, v131
	v_mul_f32_e32 v133, v159, v118
	v_add_f32_e32 v131, v131, v133
	v_mul_f32_e32 v132, 0xbfb8aa3b, v131
	v_exp_f32_e32 v132, v132
	v_add_f32_e32 v108, 1.0, v108
	v_rcp_f32_e32 v108, v108
	v_mul_f32_e32 v102, v102, v106
	v_cvt_pk_bf16_f32 v102, v102, v102
	ds_write_b16 v112, v102 offset:6528
	v_mul_f32_e32 v133, v161, v120
	v_add_f32_e32 v102, v153, v133
	v_mul_f32_e32 v133, v160, v119
	v_add_f32_e32 v102, v133, v102
	v_mul_f32_e32 v133, v158, v118
	v_add_f32_e32 v102, v133, v102
	v_mul_f32_e32 v133, v159, v117
	v_add_f32_e32 v102, v102, v133
	v_mul_f32_e32 v106, 0xbfb8aa3b, v102
	v_exp_f32_e32 v106, v106
	v_add_f32_e32 v132, 1.0, v132
	v_rcp_f32_e32 v132, v132
	v_mul_f32_e32 v107, v107, v108
	v_cvt_pk_bf16_f32 v107, v107, v107
	ds_write_b16 v112, v107 offset:6256
	v_mul_f32_e32 v133, v161, v119
	v_add_f32_e32 v107, v153, v133
	v_mul_f32_e32 v133, v160, v118
	v_add_f32_e32 v107, v133, v107
	v_mul_f32_e32 v133, v158, v117
	v_add_f32_e32 v107, v133, v107
	v_mul_f32_e32 v133, v159, v116
	v_add_f32_e32 v107, v107, v133
	v_mul_f32_e32 v108, 0xbfb8aa3b, v107
	v_exp_f32_e32 v108, v108
	v_add_f32_e32 v106, 1.0, v106
	v_rcp_f32_e32 v106, v106
	v_mul_f32_e32 v131, v131, v132
	v_cvt_pk_bf16_f32 v131, v131, v131
	ds_write_b16 v112, v131 offset:5984
	ds_read_u16 v127, v112 offset:3264
	ds_read_u16 v126, v112 offset:2992
	ds_read_u16 v125, v112 offset:2720
	ds_read_u16 v124, v112 offset:2448
	ds_read_u16 v123, v112 offset:2176
	ds_read_u16 v122, v112 offset:1904
	ds_read_u16 v121, v112 offset:1632
	ds_read_u16 v120, v112 offset:1360
	v_mul_f32_e32 v133, v161, v118
	v_add_f32_e32 v131, v153, v133
	v_mul_f32_e32 v133, v160, v117
	v_add_f32_e32 v131, v133, v131
	v_mul_f32_e32 v133, v158, v116
	v_add_f32_e32 v131, v133, v131
	v_mul_f32_e32 v133, v159, v115
	v_add_f32_e32 v131, v131, v133
	v_mul_f32_e32 v132, 0xbfb8aa3b, v131
	v_exp_f32_e32 v132, v132
	v_add_f32_e32 v108, 1.0, v108
	v_rcp_f32_e32 v108, v108
	v_mul_f32_e32 v102, v102, v106
	v_cvt_pk_bf16_f32 v102, v102, v102
	ds_write_b16 v112, v102 offset:5712
	v_mul_f32_e32 v133, v161, v117
	v_add_f32_e32 v102, v153, v133
	v_mul_f32_e32 v133, v160, v116
	v_add_f32_e32 v102, v133, v102
	v_mul_f32_e32 v133, v158, v115
	v_add_f32_e32 v102, v133, v102
	v_mul_f32_e32 v133, v159, v130
	v_add_f32_e32 v102, v102, v133
	v_mul_f32_e32 v106, 0xbfb8aa3b, v102
	v_exp_f32_e32 v106, v106
	v_add_f32_e32 v132, 1.0, v132
	v_rcp_f32_e32 v132, v132
	v_mul_f32_e32 v107, v107, v108
	v_cvt_pk_bf16_f32 v107, v107, v107
	ds_write_b16 v112, v107 offset:5440
	v_mul_f32_e32 v133, v161, v116
	v_add_f32_e32 v107, v153, v133
	v_mul_f32_e32 v133, v160, v115
	v_add_f32_e32 v107, v133, v107
	v_mul_f32_e32 v133, v158, v130
	v_add_f32_e32 v107, v133, v107
	v_mul_f32_e32 v133, v159, v129
	v_add_f32_e32 v107, v107, v133
	v_mul_f32_e32 v108, 0xbfb8aa3b, v107
	v_exp_f32_e32 v108, v108
	v_add_f32_e32 v106, 1.0, v106
	v_rcp_f32_e32 v106, v106
	v_mul_f32_e32 v131, v131, v132
	v_cvt_pk_bf16_f32 v131, v131, v131
	ds_write_b16 v112, v131 offset:5168
	v_mul_f32_e32 v133, v161, v115
	v_add_f32_e32 v131, v153, v133
	v_mul_f32_e32 v133, v160, v130
	v_add_f32_e32 v131, v133, v131
	v_mul_f32_e32 v133, v158, v129
	v_add_f32_e32 v131, v133, v131
	v_mul_f32_e32 v133, v159, v128
	v_add_f32_e32 v131, v131, v133
	v_mul_f32_e32 v132, 0xbfb8aa3b, v131
	v_exp_f32_e32 v132, v132
	v_add_f32_e32 v108, 1.0, v108
	v_rcp_f32_e32 v108, v108
	v_mul_f32_e32 v102, v102, v106
	v_cvt_pk_bf16_f32 v102, v102, v102
	ds_write_b16 v112, v102 offset:4896
	s_waitcnt lgkmcnt(0)
; __device__ __forceinline__ float bf2f(u16 h) { return __uint_as_float(((uint32_t)h) << 16); }
; __device__ __forceinline__ float siluf(float x) { return x * __builtin_amdgcn_rcpf(1.f + __builtin_amdgcn_exp2f(x * -1.4426950408889634f)); }
; __device__ __forceinline__ void ssd_phase(const Params& p, int j, char* smem) {
;     ...
;         const float nh2 = bf2f(colp[(CL - 1) * cld]), nh1 = bf2f(colp[(CL - 2) * cld]), nh0 = bf2f(colp[(CL - 3) * cld]);
;         float a = bf2f(colp[63 * cld]), b1 = bf2f(colp[62 * cld]), c1 = bf2f(colp[61 * cld]);
; #pragma unroll 8
;         for (int s = 63; s >= 3; --s) {
;           const float d = bf2f(colp[(s - 3) * cld]);
;           float o = siluf(cbias + cw3 * a + cw2 * b1 + cw1 * c1 + cw0 * d);
;           if (s >= CL) o = 0.f;
;           colp[s * cld] = f2bf(o);
;           a = b1; b1 = c1; c1 = d;
;         }
	v_lshlrev_b32_e32 v127, 16, v127
	v_lshlrev_b32_e32 v126, 16, v126
	v_lshlrev_b32_e32 v125, 16, v125
	v_lshlrev_b32_e32 v124, 16, v124
	v_lshlrev_b32_e32 v123, 16, v123
	v_lshlrev_b32_e32 v122, 16, v122
	v_lshlrev_b32_e32 v121, 16, v121
	v_lshlrev_b32_e32 v120, 16, v120
	v_mul_f32_e32 v133, v161, v130
	v_add_f32_e32 v102, v153, v133
	v_mul_f32_e32 v133, v160, v129
	v_add_f32_e32 v102, v133, v102
	v_mul_f32_e32 v133, v158, v128
	v_add_f32_e32 v102, v133, v102
	v_mul_f32_e32 v133, v159, v127
	v_add_f32_e32 v102, v102, v133
	v_mul_f32_e32 v106, 0xbfb8aa3b, v102
	v_exp_f32_e32 v106, v106
	v_add_f32_e32 v132, 1.0, v132
	v_rcp_f32_e32 v132, v132
	v_mul_f32_e32 v107, v107, v108
	v_cvt_pk_bf16_f32 v107, v107, v107
	ds_write_b16 v112, v107 offset:4624
	v_mul_f32_e32 v133, v161, v129
	v_add_f32_e32 v107, v153, v133
	v_mul_f32_e32 v133, v160, v128
	v_add_f32_e32 v107, v133, v107
	v_mul_f32_e32 v133, v158, v127
	v_add_f32_e32 v107, v133, v107
	v_mul_f32_e32 v133, v159, v126
	v_add_f32_e32 v107, v107, v133
	v_mul_f32_e32 v108, 0xbfb8aa3b, v107
	v_exp_f32_e32 v108, v108
	v_add_f32_e32 v106, 1.0, v106
	v_rcp_f32_e32 v106, v106
	v_mul_f32_e32 v131, v131, v132
	v_cvt_pk_bf16_f32 v131, v131, v131
	ds_write_b16 v112, v131 offset:4352
	v_mul_f32_e32 v133, v161, v128
	v_add_f32_e32 v131, v153, v133
	v_mul_f32_e32 v133, v160, v127
	v_add_f32_e32 v131, v133, v131
	v_mul_f32_e32 v133, v158, v126
	v_add_f32_e32 v131, v133, v131
	v_mul_f32_e32 v133, v159, v125
	v_add_f32_e32 v131, v131, v133
	v_mul_f32_e32 v132, 0xbfb8aa3b, v131
	v_exp_f32_e32 v132, v132
	v_add_f32_e32 v108, 1.0, v108
	v_rcp_f32_e32 v108, v108
	v_mul_f32_e32 v102, v102, v106
	v_cvt_pk_bf16_f32 v102, v102, v102
	ds_write_b16 v112, v102 offset:4080
	v_mul_f32_e32 v133, v161, v127
	v_add_f32_e32 v102, v153, v133
	v_mul_f32_e32 v133, v160, v126
	v_add_f32_e32 v102, v133, v102
	v_mul_f32_e32 v133, v158, v125
	v_add_f32_e32 v102, v133, v102
	v_mul_f32_e32 v133, v159, v124
	v_add_f32_e32 v102, v102, v133
	v_mul_f32_e32 v106, 0xbfb8aa3b, v102
	v_exp_f32_e32 v106, v106
	v_add_f32_e32 v132, 1.0, v132
	v_rcp_f32_e32 v132, v132
	v_mul_f32_e32 v107, v107, v108
	v_cvt_pk_bf16_f32 v107, v107, v107
	ds_write_b16 v112, v107 offset:3808
	ds_read_u16 v119, v112 offset:1088
	ds_read_u16 v118, v112 offset:816
	ds_read_u16 v117, v112 offset:544
	ds_read_u16 v116, v112 offset:272
	ds_read_u16 v115, v112 offset:0
	v_mul_f32_e32 v133, v161, v126
	v_add_f32_e32 v107, v153, v133
	v_mul_f32_e32 v133, v160, v125
	v_add_f32_e32 v107, v133, v107
	v_mul_f32_e32 v133, v158, v124
	v_add_f32_e32 v107, v133, v107
	v_mul_f32_e32 v133, v159, v123
	v_add_f32_e32 v107, v107, v133
	v_mul_f32_e32 v108, 0xbfb8aa3b, v107
	v_exp_f32_e32 v108, v108
	v_add_f32_e32 v106, 1.0, v106
	v_rcp_f32_e32 v106, v106
	v_mul_f32_e32 v131, v131, v132
	v_cvt_pk_bf16_f32 v131, v131, v131
	ds_write_b16 v112, v131 offset:3536
	v_mul_f32_e32 v133, v161, v125
	v_add_f32_e32 v131, v153, v133
	v_mul_f32_e32 v133, v160, v124
	v_add_f32_e32 v131, v133, v131
	v_mul_f32_e32 v133, v158, v123
	v_add_f32_e32 v131, v133, v131
	v_mul_f32_e32 v133, v159, v122
	v_add_f32_e32 v131, v131, v133
	v_mul_f32_e32 v132, 0xbfb8aa3b, v131
	v_exp_f32_e32 v132, v132
	v_add_f32_e32 v108, 1.0, v108
	v_rcp_f32_e32 v108, v108
	v_mul_f32_e32 v102, v102, v106
	v_cvt_pk_bf16_f32 v102, v102, v102
	ds_write_b16 v112, v102 offset:3264
	v_mul_f32_e32 v133, v161, v124
	v_add_f32_e32 v102, v153, v133
	v_mul_f32_e32 v133, v160, v123
	v_add_f32_e32 v102, v133, v102
	v_mul_f32_e32 v133, v158, v122
	v_add_f32_e32 v102, v133, v102
	v_mul_f32_e32 v133, v159, v121
	v_add_f32_e32 v102, v102, v133
	v_mul_f32_e32 v106, 0xbfb8aa3b, v102
	v_exp_f32_e32 v106, v106
	v_add_f32_e32 v132, 1.0, v132
	v_rcp_f32_e32 v132, v132
	v_mul_f32_e32 v107, v107, v108
	v_cvt_pk_bf16_f32 v107, v107, v107
	ds_write_b16 v112, v107 offset:2992
	v_mul_f32_e32 v133, v161, v123
	v_add_f32_e32 v107, v153, v133
	v_mul_f32_e32 v133, v160, v122
	v_add_f32_e32 v107, v133, v107
	v_mul_f32_e32 v133, v158, v121
	v_add_f32_e32 v107, v133, v107
	v_mul_f32_e32 v133, v159, v120
	v_add_f32_e32 v107, v107, v133
	v_mul_f32_e32 v108, 0xbfb8aa3b, v107
	v_exp_f32_e32 v108, v108
	v_add_f32_e32 v106, 1.0, v106
	v_rcp_f32_e32 v106, v106
	v_mul_f32_e32 v131, v131, v132
	v_cvt_pk_bf16_f32 v131, v131, v131
	ds_write_b16 v112, v131 offset:2720
	s_waitcnt lgkmcnt(0)
; __device__ __forceinline__ float bf2f(u16 h) { return __uint_as_float(((uint32_t)h) << 16); }
; __device__ __forceinline__ float siluf(float x) { return x * __builtin_amdgcn_rcpf(1.f + __builtin_amdgcn_exp2f(x * -1.4426950408889634f)); }
; __device__ __forceinline__ void ssd_phase(const Params& p, int j, char* smem) {
;     ...
;         for (int s = 63; s >= 3; --s) {
;           const float d = bf2f(colp[(s - 3) * cld]);
;           float o = siluf(cbias + cw3 * a + cw2 * b1 + cw1 * c1 + cw0 * d);
;           if (s >= CL) o = 0.f;
;           colp[s * cld] = f2bf(o);
;           a = b1; b1 = c1; c1 = d;
;         }
;         colp[2 * cld] = f2bf(siluf(cbias + cw3 * a + cw2 * b1 + cw1 * c1 + cw0 * hl2));
;         colp[1 * cld] = f2bf(siluf(cbias + cw3 * b1 + cw2 * c1 + cw1 * hl2 + cw0 * hl1));
;         colp[0] = f2bf(siluf(cbias + cw3 * c1 + cw2 * hl2 + cw1 * hl1 + cw0 * hl0));
;         hl0 = nh0; hl1 = nh1; hl2 = nh2;
	v_lshlrev_b32_e32 v119, 16, v119
	v_lshlrev_b32_e32 v118, 16, v118
	v_lshlrev_b32_e32 v117, 16, v117
	v_lshlrev_b32_e32 v116, 16, v116
	v_lshlrev_b32_e32 v115, 16, v115
	v_mul_f32_e32 v133, v161, v122
	v_add_f32_e32 v131, v153, v133
	v_mul_f32_e32 v133, v160, v121
	v_add_f32_e32 v131, v133, v131
	v_mul_f32_e32 v133, v158, v120
	v_add_f32_e32 v131, v133, v131
	v_mul_f32_e32 v133, v159, v119
	v_add_f32_e32 v131, v131, v133
	v_mul_f32_e32 v132, 0xbfb8aa3b, v131
	v_exp_f32_e32 v132, v132
	v_add_f32_e32 v108, 1.0, v108
	v_rcp_f32_e32 v108, v108
	v_mul_f32_e32 v102, v102, v106
	v_cvt_pk_bf16_f32 v102, v102, v102
	ds_write_b16 v112, v102 offset:2448
	v_mul_f32_e32 v133, v161, v121
	v_add_f32_e32 v102, v153, v133
	v_mul_f32_e32 v133, v160, v120
	v_add_f32_e32 v102, v133, v102
	v_mul_f32_e32 v133, v158, v119
	v_add_f32_e32 v102, v133, v102
	v_mul_f32_e32 v133, v159, v118
	v_add_f32_e32 v102, v102, v133
	v_mul_f32_e32 v106, 0xbfb8aa3b, v102
	v_exp_f32_e32 v106, v106
	v_add_f32_e32 v132, 1.0, v132
	v_rcp_f32_e32 v132, v132
	v_mul_f32_e32 v107, v107, v108
	v_cvt_pk_bf16_f32 v107, v107, v107
	ds_write_b16 v112, v107 offset:2176
	v_mul_f32_e32 v133, v161, v120
	v_add_f32_e32 v107, v153, v133
	v_mul_f32_e32 v133, v160, v119
	v_add_f32_e32 v107, v133, v107
	v_mul_f32_e32 v133, v158, v118
	v_add_f32_e32 v107, v133, v107
	v_mul_f32_e32 v133, v159, v117
	v_add_f32_e32 v107, v107, v133
	v_mul_f32_e32 v108, 0xbfb8aa3b, v107
	v_exp_f32_e32 v108, v108
	v_add_f32_e32 v106, 1.0, v106
	v_rcp_f32_e32 v106, v106
	v_mul_f32_e32 v131, v131, v132
	v_cvt_pk_bf16_f32 v131, v131, v131
	ds_write_b16 v112, v131 offset:1904
	v_mul_f32_e32 v133, v161, v119
	v_add_f32_e32 v131, v153, v133
	v_mul_f32_e32 v133, v160, v118
	v_add_f32_e32 v131, v133, v131
	v_mul_f32_e32 v133, v158, v117
	v_add_f32_e32 v131, v133, v131
	v_mul_f32_e32 v133, v159, v116
	v_add_f32_e32 v131, v131, v133
	v_mul_f32_e32 v132, 0xbfb8aa3b, v131
	v_exp_f32_e32 v132, v132
	v_add_f32_e32 v108, 1.0, v108
	v_rcp_f32_e32 v108, v108
	v_mul_f32_e32 v102, v102, v106
	v_cvt_pk_bf16_f32 v102, v102, v102
	ds_write_b16 v112, v102 offset:1632
	v_mul_f32_e32 v133, v161, v118
	v_add_f32_e32 v102, v153, v133
	v_mul_f32_e32 v133, v160, v117
	v_add_f32_e32 v102, v133, v102
	v_mul_f32_e32 v133, v158, v116
	v_add_f32_e32 v102, v133, v102
	v_mul_f32_e32 v133, v159, v115
	v_add_f32_e32 v102, v102, v133
	v_mul_f32_e32 v106, 0xbfb8aa3b, v102
	v_exp_f32_e32 v106, v106
	v_add_f32_e32 v132, 1.0, v132
	v_rcp_f32_e32 v132, v132
	v_mul_f32_e32 v107, v107, v108
	v_cvt_pk_bf16_f32 v107, v107, v107
	ds_write_b16 v112, v107 offset:1360
	v_add_f32_e32 v106, 1.0, v106
	v_rcp_f32_e32 v106, v106
	v_mul_f32_e32 v131, v131, v132
	v_cvt_pk_bf16_f32 v131, v131, v131
	ds_write_b16 v112, v131 offset:1088
	v_mul_f32_e32 v102, v102, v106
	v_cvt_pk_bf16_f32 v102, v102, v102
	ds_write_b16 v112, v102 offset:816
	v_mov_b32_e32 v103, v117
	v_mov_b32_e32 v104, v116
	v_mov_b32_e32 v105, v115
	s_branch .LBB0_254
.Lmy_conv_x:
	v_mov_b32_e32 v130, v109
	v_mov_b32_e32 v129, v108
	v_mov_b32_e32 v128, v106
	ds_read_u16 v127, v112 offset:31680
	ds_read_u16 v126, v112 offset:31152
	ds_read_u16 v125, v112 offset:30624
	ds_read_u16 v124, v112 offset:30096
	ds_read_u16 v123, v112 offset:29568
	ds_read_u16 v122, v112 offset:29040
	ds_read_u16 v121, v112 offset:28512
	ds_read_u16 v120, v112 offset:27984
	s_waitcnt lgkmcnt(0)
	v_lshlrev_b32_e32 v127, 16, v127
	v_lshlrev_b32_e32 v126, 16, v126
	v_lshlrev_b32_e32 v125, 16, v125
	v_lshlrev_b32_e32 v124, 16, v124
	v_lshlrev_b32_e32 v123, 16, v123
	v_lshlrev_b32_e32 v122, 16, v122
	v_lshlrev_b32_e32 v121, 16, v121
	v_lshlrev_b32_e32 v120, 16, v120
	v_mul_f32_e32 v133, v161, v130
	v_add_f32_e32 v102, v153, v133
	v_mul_f32_e32 v133, v160, v129
	v_add_f32_e32 v102, v133, v102
	v_mul_f32_e32 v133, v158, v128
	v_add_f32_e32 v102, v133, v102
	v_mul_f32_e32 v133, v159, v127
	v_add_f32_e32 v102, v102, v133
	v_mul_f32_e32 v106, 0xbfb8aa3b, v102
	v_exp_f32_e32 v106, v106
	v_mul_f32_e32 v133, v161, v129
	v_add_f32_e32 v107, v153, v133
	v_mul_f32_e32 v133, v160, v128
	v_add_f32_e32 v107, v133, v107
	v_mul_f32_e32 v133, v158, v127
	v_add_f32_e32 v107, v133, v107
	v_mul_f32_e32 v133, v159, v126
	v_add_f32_e32 v107, v107, v133
	v_mul_f32_e32 v108, 0xbfb8aa3b, v107
	v_exp_f32_e32 v108, v108
	v_add_f32_e32 v106, 1.0, v106
	v_rcp_f32_e32 v106, v106
	v_mul_f32_e32 v133, v161, v128
	v_add_f32_e32 v131, v153, v133
	v_mul_f32_e32 v133, v160, v127
	v_add_f32_e32 v131, v133, v131
	v_mul_f32_e32 v133, v158, v126
	v_add_f32_e32 v131, v133, v131
	v_mul_f32_e32 v133, v159, v125
	v_add_f32_e32 v131, v131, v133
	v_mul_f32_e32 v132, 0xbfb8aa3b, v131
	v_exp_f32_e32 v132, v132
	v_add_f32_e32 v108, 1.0, v108
	v_rcp_f32_e32 v108, v108
	v_mul_f32_e32 v102, v102, v106
	v_cvt_pk_bf16_f32 v102, v102, v102
	ds_write_b16 v112, v102 offset:33264
	v_mul_f32_e32 v133, v161, v127
	v_add_f32_e32 v102, v153, v133
	v_mul_f32_e32 v133, v160, v126
	v_add_f32_e32 v102, v133, v102
	v_mul_f32_e32 v133, v158, v125
	v_add_f32_e32 v102, v133, v102
	v_mul_f32_e32 v133, v159, v124
	v_add_f32_e32 v102, v102, v133
	v_mul_f32_e32 v106, 0xbfb8aa3b, v102
	v_exp_f32_e32 v106, v106
	v_add_f32_e32 v132, 1.0, v132
	v_rcp_f32_e32 v132, v132
	v_mul_f32_e32 v107, v107, v108
	v_cvt_pk_bf16_f32 v107, v107, v107
	ds_write_b16 v112, v107 offset:32736
	ds_read_u16 v119, v112 offset:27456
	ds_read_u16 v118, v112 offset:26928
	ds_read_u16 v117, v112 offset:26400
	ds_read_u16 v116, v112 offset:25872
	ds_read_u16 v115, v112 offset:25344
	ds_read_u16 v130, v112 offset:24816
	ds_read_u16 v129, v112 offset:24288
	ds_read_u16 v128, v112 offset:23760
	v_mul_f32_e32 v133, v161, v126
	v_add_f32_e32 v107, v153, v133
; __device__ __forceinline__ float bf2f(u16 h) { return __uint_as_float(((uint32_t)h) << 16); }
; __device__ __forceinline__ float siluf(float x) { return x * __builtin_amdgcn_rcpf(1.f + __builtin_amdgcn_exp2f(x * -1.4426950408889634f)); }
; __device__ __forceinline__ void ssd_phase(const Params& p, int j, char* smem) {
;     ...
;         const float nh2 = bf2f(colp[(CL - 1) * cld]), nh1 = bf2f(colp[(CL - 2) * cld]), nh0 = bf2f(colp[(CL - 3) * cld]);
;         float a = bf2f(colp[63 * cld]), b1 = bf2f(colp[62 * cld]), c1 = bf2f(colp[61 * cld]);
; #pragma unroll 8
;         for (int s = 63; s >= 3; --s) {
;           const float d = bf2f(colp[(s - 3) * cld]);
;           float o = siluf(cbias + cw3 * a + cw2 * b1 + cw1 * c1 + cw0 * d);
;           if (s >= CL) o = 0.f;
;           colp[s * cld] = f2bf(o);
;           a = b1; b1 = c1; c1 = d;
;         }
	v_mul_f32_e32 v133, v160, v125
	v_add_f32_e32 v107, v133, v107
	v_mul_f32_e32 v133, v158, v124
	v_add_f32_e32 v107, v133, v107
	v_mul_f32_e32 v133, v159, v123
	v_add_f32_e32 v107, v107, v133
	v_mul_f32_e32 v108, 0xbfb8aa3b, v107
	v_exp_f32_e32 v108, v108
	v_add_f32_e32 v106, 1.0, v106
	v_rcp_f32_e32 v106, v106
	v_mul_f32_e32 v131, v131, v132
	v_cvt_pk_bf16_f32 v131, v131, v131
	ds_write_b16 v112, v131 offset:32208
	v_mul_f32_e32 v133, v161, v125
	v_add_f32_e32 v131, v153, v133
	v_mul_f32_e32 v133, v160, v124
	v_add_f32_e32 v131, v133, v131
	v_mul_f32_e32 v133, v158, v123
	v_add_f32_e32 v131, v133, v131
	v_mul_f32_e32 v133, v159, v122
	v_add_f32_e32 v131, v131, v133
	v_mul_f32_e32 v132, 0xbfb8aa3b, v131
	v_exp_f32_e32 v132, v132
	v_add_f32_e32 v108, 1.0, v108
	v_rcp_f32_e32 v108, v108
	v_mul_f32_e32 v102, v102, v106
	v_cvt_pk_bf16_f32 v102, v102, v102
	ds_write_b16 v112, v102 offset:31680
	v_mul_f32_e32 v133, v161, v124
	v_add_f32_e32 v102, v153, v133
	v_mul_f32_e32 v133, v160, v123
	v_add_f32_e32 v102, v133, v102
	v_mul_f32_e32 v133, v158, v122
	v_add_f32_e32 v102, v133, v102
	v_mul_f32_e32 v133, v159, v121
	v_add_f32_e32 v102, v102, v133
	v_mul_f32_e32 v106, 0xbfb8aa3b, v102
	v_exp_f32_e32 v106, v106
	v_add_f32_e32 v132, 1.0, v132
	v_rcp_f32_e32 v132, v132
	v_mul_f32_e32 v107, v107, v108
	v_cvt_pk_bf16_f32 v107, v107, v107
	ds_write_b16 v112, v107 offset:31152
	v_mul_f32_e32 v133, v161, v123
	v_add_f32_e32 v107, v153, v133
	v_mul_f32_e32 v133, v160, v122
	v_add_f32_e32 v107, v133, v107
	v_mul_f32_e32 v133, v158, v121
	v_add_f32_e32 v107, v133, v107
	v_mul_f32_e32 v133, v159, v120
	v_add_f32_e32 v107, v107, v133
	v_mul_f32_e32 v108, 0xbfb8aa3b, v107
	v_exp_f32_e32 v108, v108
	v_add_f32_e32 v106, 1.0, v106
	v_rcp_f32_e32 v106, v106
	v_mul_f32_e32 v131, v131, v132
	v_cvt_pk_bf16_f32 v131, v131, v131
	ds_write_b16 v112, v131 offset:30624
	s_waitcnt lgkmcnt(0)
	v_lshlrev_b32_e32 v119, 16, v119
	v_lshlrev_b32_e32 v118, 16, v118
	v_lshlrev_b32_e32 v117, 16, v117
	v_lshlrev_b32_e32 v116, 16, v116
	v_lshlrev_b32_e32 v115, 16, v115
	v_lshlrev_b32_e32 v130, 16, v130
	v_lshlrev_b32_e32 v129, 16, v129
	v_lshlrev_b32_e32 v128, 16, v128
	v_mul_f32_e32 v133, v161, v122
	v_add_f32_e32 v131, v153, v133
	v_mul_f32_e32 v133, v160, v121
	v_add_f32_e32 v131, v133, v131
	v_mul_f32_e32 v133, v158, v120
	v_add_f32_e32 v131, v133, v131
	v_mul_f32_e32 v133, v159, v119
	v_add_f32_e32 v131, v131, v133
	v_mul_f32_e32 v132, 0xbfb8aa3b, v131
	v_exp_f32_e32 v132, v132
	v_add_f32_e32 v108, 1.0, v108
	v_rcp_f32_e32 v108, v108
	v_mul_f32_e32 v102, v102, v106
	v_cvt_pk_bf16_f32 v102, v102, v102
	ds_write_b16 v112, v102 offset:30096
	v_mul_f32_e32 v133, v161, v121
	v_add_f32_e32 v102, v153, v133
	v_mul_f32_e32 v133, v160, v120
	v_add_f32_e32 v102, v133, v102
	v_mul_f32_e32 v133, v158, v119
	v_add_f32_e32 v102, v133, v102
	v_mul_f32_e32 v133, v159, v118
	v_add_f32_e32 v102, v102, v133
	v_mul_f32_e32 v106, 0xbfb8aa3b, v102
	v_exp_f32_e32 v106, v106
	v_add_f32_e32 v132, 1.0, v132
	v_rcp_f32_e32 v132, v132
	v_mul_f32_e32 v107, v107, v108
	v_cvt_pk_bf16_f32 v107, v107, v107
	ds_write_b16 v112, v107 offset:29568
	v_mul_f32_e32 v133, v161, v120
	v_add_f32_e32 v107, v153, v133
	v_mul_f32_e32 v133, v160, v119
	v_add_f32_e32 v107, v133, v107
	v_mul_f32_e32 v133, v158, v118
	v_add_f32_e32 v107, v133, v107
	v_mul_f32_e32 v133, v159, v117
	v_add_f32_e32 v107, v107, v133
	v_mul_f32_e32 v108, 0xbfb8aa3b, v107
	v_exp_f32_e32 v108, v108
	v_add_f32_e32 v106, 1.0, v106
	v_rcp_f32_e32 v106, v106
	v_mul_f32_e32 v131, v131, v132
	v_cvt_pk_bf16_f32 v131, v131, v131
	ds_write_b16 v112, v131 offset:29040
	v_mul_f32_e32 v133, v161, v119
	v_add_f32_e32 v131, v153, v133
	v_mul_f32_e32 v133, v160, v118
	v_add_f32_e32 v131, v133, v131
	v_mul_f32_e32 v133, v158, v117
	v_add_f32_e32 v131, v133, v131
	v_mul_f32_e32 v133, v159, v116
	v_add_f32_e32 v131, v131, v133
	v_mul_f32_e32 v132, 0xbfb8aa3b, v131
	v_exp_f32_e32 v132, v132
	v_add_f32_e32 v108, 1.0, v108
	v_rcp_f32_e32 v108, v108
	v_mul_f32_e32 v102, v102, v106
	v_cvt_pk_bf16_f32 v102, v102, v102
	ds_write_b16 v112, v102 offset:28512
	ds_read_u16 v127, v112 offset:23232
	ds_read_u16 v126, v112 offset:22704
	ds_read_u16 v125, v112 offset:22176
	ds_read_u16 v124, v112 offset:21648
	ds_read_u16 v123, v112 offset:21120
	ds_read_u16 v122, v112 offset:20592
	ds_read_u16 v121, v112 offset:20064
	ds_read_u16 v120, v112 offset:19536
	v_mul_f32_e32 v133, v161, v118
	v_add_f32_e32 v102, v153, v133
	v_mul_f32_e32 v133, v160, v117
	v_add_f32_e32 v102, v133, v102
	v_mul_f32_e32 v133, v158, v116
	v_add_f32_e32 v102, v133, v102
	v_mul_f32_e32 v133, v159, v115
	v_add_f32_e32 v102, v102, v133
	v_mul_f32_e32 v106, 0xbfb8aa3b, v102
	v_exp_f32_e32 v106, v106
	v_add_f32_e32 v132, 1.0, v132
	v_rcp_f32_e32 v132, v132
	v_mul_f32_e32 v107, v107, v108
	v_cvt_pk_bf16_f32 v107, v107, v107
	ds_write_b16 v112, v107 offset:27984
	v_mul_f32_e32 v133, v161, v117
	v_add_f32_e32 v107, v153, v133
	v_mul_f32_e32 v133, v160, v116
	v_add_f32_e32 v107, v133, v107
	v_mul_f32_e32 v133, v158, v115
	v_add_f32_e32 v107, v133, v107
	v_mul_f32_e32 v133, v159, v130
	v_add_f32_e32 v107, v107, v133
	v_mul_f32_e32 v108, 0xbfb8aa3b, v107
	v_exp_f32_e32 v108, v108
	v_add_f32_e32 v106, 1.0, v106
	v_rcp_f32_e32 v106, v106
	v_mul_f32_e32 v131, v131, v132
	v_cvt_pk_bf16_f32 v131, v131, v131
	ds_write_b16 v112, v131 offset:27456
	v_mul_f32_e32 v133, v161, v116
	v_add_f32_e32 v131, v153, v133
	v_mul_f32_e32 v133, v160, v115
	v_add_f32_e32 v131, v133, v131
	v_mul_f32_e32 v133, v158, v130
	v_add_f32_e32 v131, v133, v131
	v_mul_f32_e32 v133, v159, v129
	v_add_f32_e32 v131, v131, v133
	v_mul_f32_e32 v132, 0xbfb8aa3b, v131
	v_exp_f32_e32 v132, v132
	v_add_f32_e32 v108, 1.0, v108
	v_rcp_f32_e32 v108, v108
	v_mul_f32_e32 v102, v102, v106
	v_cvt_pk_bf16_f32 v102, v102, v102
	ds_write_b16 v112, v102 offset:26928
	v_mul_f32_e32 v133, v161, v115
	v_add_f32_e32 v102, v153, v133
	v_mul_f32_e32 v133, v160, v130
	v_add_f32_e32 v102, v133, v102
	v_mul_f32_e32 v133, v158, v129
	v_add_f32_e32 v102, v133, v102
	v_mul_f32_e32 v133, v159, v128
	v_add_f32_e32 v102, v102, v133
	v_mul_f32_e32 v106, 0xbfb8aa3b, v102
	v_exp_f32_e32 v106, v106
	v_add_f32_e32 v132, 1.0, v132
	v_rcp_f32_e32 v132, v132
	v_mul_f32_e32 v107, v107, v108
	v_cvt_pk_bf16_f32 v107, v107, v107
	ds_write_b16 v112, v107 offset:26400
	s_waitcnt lgkmcnt(0)
; __device__ __forceinline__ float bf2f(u16 h) { return __uint_as_float(((uint32_t)h) << 16); }
; __device__ __forceinline__ float siluf(float x) { return x * __builtin_amdgcn_rcpf(1.f + __builtin_amdgcn_exp2f(x * -1.4426950408889634f)); }
; __device__ __forceinline__ void ssd_phase(const Params& p, int j, char* smem) {
;     ...
;         const float nh2 = bf2f(colp[(CL - 1) * cld]), nh1 = bf2f(colp[(CL - 2) * cld]), nh0 = bf2f(colp[(CL - 3) * cld]);
;         float a = bf2f(colp[63 * cld]), b1 = bf2f(colp[62 * cld]), c1 = bf2f(colp[61 * cld]);
; #pragma unroll 8
;         for (int s = 63; s >= 3; --s) {
;           const float d = bf2f(colp[(s - 3) * cld]);
;           float o = siluf(cbias + cw3 * a + cw2 * b1 + cw1 * c1 + cw0 * d);
;           if (s >= CL) o = 0.f;
;           colp[s * cld] = f2bf(o);
;           a = b1; b1 = c1; c1 = d;
;         }
	v_lshlrev_b32_e32 v127, 16, v127
	v_lshlrev_b32_e32 v126, 16, v126
	v_lshlrev_b32_e32 v125, 16, v125
	v_lshlrev_b32_e32 v124, 16, v124
	v_lshlrev_b32_e32 v123, 16, v123
	v_lshlrev_b32_e32 v122, 16, v122
	v_lshlrev_b32_e32 v121, 16, v121
	v_lshlrev_b32_e32 v120, 16, v120
	v_mul_f32_e32 v133, v161, v130
	v_add_f32_e32 v107, v153, v133
	v_mul_f32_e32 v133, v160, v129
	v_add_f32_e32 v107, v133, v107
	v_mul_f32_e32 v133, v158, v128
	v_add_f32_e32 v107, v133, v107
	v_mul_f32_e32 v133, v159, v127
	v_add_f32_e32 v107, v107, v133
	v_mul_f32_e32 v108, 0xbfb8aa3b, v107
	v_exp_f32_e32 v108, v108
	v_add_f32_e32 v106, 1.0, v106
	v_rcp_f32_e32 v106, v106
	v_mul_f32_e32 v131, v131, v132
	v_cvt_pk_bf16_f32 v131, v131, v131
	ds_write_b16 v112, v131 offset:25872
	v_mul_f32_e32 v133, v161, v129
	v_add_f32_e32 v131, v153, v133
	v_mul_f32_e32 v133, v160, v128
	v_add_f32_e32 v131, v133, v131
	v_mul_f32_e32 v133, v158, v127
	v_add_f32_e32 v131, v133, v131
	v_mul_f32_e32 v133, v159, v126
	v_add_f32_e32 v131, v131, v133
	v_mul_f32_e32 v132, 0xbfb8aa3b, v131
	v_exp_f32_e32 v132, v132
	v_add_f32_e32 v108, 1.0, v108
	v_rcp_f32_e32 v108, v108
	v_mul_f32_e32 v102, v102, v106
	v_cvt_pk_bf16_f32 v102, v102, v102
	ds_write_b16 v112, v102 offset:25344
	v_mul_f32_e32 v133, v161, v128
	v_add_f32_e32 v102, v153, v133
	v_mul_f32_e32 v133, v160, v127
	v_add_f32_e32 v102, v133, v102
	v_mul_f32_e32 v133, v158, v126
	v_add_f32_e32 v102, v133, v102
	v_mul_f32_e32 v133, v159, v125
	v_add_f32_e32 v102, v102, v133
	v_mul_f32_e32 v106, 0xbfb8aa3b, v102
	v_exp_f32_e32 v106, v106
	v_add_f32_e32 v132, 1.0, v132
	v_rcp_f32_e32 v132, v132
	v_mul_f32_e32 v107, v107, v108
	v_cvt_pk_bf16_f32 v107, v107, v107
	ds_write_b16 v112, v107 offset:24816
	v_mul_f32_e32 v133, v161, v127
	v_add_f32_e32 v107, v153, v133
	v_mul_f32_e32 v133, v160, v126
	v_add_f32_e32 v107, v133, v107
	v_mul_f32_e32 v133, v158, v125
	v_add_f32_e32 v107, v133, v107
	v_mul_f32_e32 v133, v159, v124
	v_add_f32_e32 v107, v107, v133
	v_mul_f32_e32 v108, 0xbfb8aa3b, v107
	v_exp_f32_e32 v108, v108
	v_add_f32_e32 v106, 1.0, v106
	v_rcp_f32_e32 v106, v106
	v_mul_f32_e32 v131, v131, v132
	v_cvt_pk_bf16_f32 v131, v131, v131
	ds_write_b16 v112, v131 offset:24288
	ds_read_u16 v119, v112 offset:19008
	ds_read_u16 v118, v112 offset:18480
	ds_read_u16 v117, v112 offset:17952
	ds_read_u16 v116, v112 offset:17424
	ds_read_u16 v115, v112 offset:16896
	ds_read_u16 v130, v112 offset:16368
	ds_read_u16 v129, v112 offset:15840
	ds_read_u16 v128, v112 offset:15312
	v_mul_f32_e32 v133, v161, v126
	v_add_f32_e32 v131, v153, v133
	v_mul_f32_e32 v133, v160, v125
	v_add_f32_e32 v131, v133, v131
	v_mul_f32_e32 v133, v158, v124
	v_add_f32_e32 v131, v133, v131
	v_mul_f32_e32 v133, v159, v123
	v_add_f32_e32 v131, v131, v133
	v_mul_f32_e32 v132, 0xbfb8aa3b, v131
	v_exp_f32_e32 v132, v132
	v_add_f32_e32 v108, 1.0, v108
	v_rcp_f32_e32 v108, v108
	v_mul_f32_e32 v102, v102, v106
	v_cvt_pk_bf16_f32 v102, v102, v102
	ds_write_b16 v112, v102 offset:23760
	v_mul_f32_e32 v133, v161, v125
	v_add_f32_e32 v102, v153, v133
	v_mul_f32_e32 v133, v160, v124
	v_add_f32_e32 v102, v133, v102
	v_mul_f32_e32 v133, v158, v123
	v_add_f32_e32 v102, v133, v102
	v_mul_f32_e32 v133, v159, v122
	v_add_f32_e32 v102, v102, v133
	v_mul_f32_e32 v106, 0xbfb8aa3b, v102
	v_exp_f32_e32 v106, v106
	v_add_f32_e32 v132, 1.0, v132
	v_rcp_f32_e32 v132, v132
	v_mul_f32_e32 v107, v107, v108
	v_cvt_pk_bf16_f32 v107, v107, v107
	ds_write_b16 v112, v107 offset:23232
	v_mul_f32_e32 v133, v161, v124
	v_add_f32_e32 v107, v153, v133
	v_mul_f32_e32 v133, v160, v123
	v_add_f32_e32 v107, v133, v107
	v_mul_f32_e32 v133, v158, v122
	v_add_f32_e32 v107, v133, v107
	v_mul_f32_e32 v133, v159, v121
	v_add_f32_e32 v107, v107, v133
	v_mul_f32_e32 v108, 0xbfb8aa3b, v107
	v_exp_f32_e32 v108, v108
	v_add_f32_e32 v106, 1.0, v106
	v_rcp_f32_e32 v106, v106
	v_mul_f32_e32 v131, v131, v132
	v_cvt_pk_bf16_f32 v131, v131, v131
	ds_write_b16 v112, v131 offset:22704
	v_mul_f32_e32 v133, v161, v123
	v_add_f32_e32 v131, v153, v133
	v_mul_f32_e32 v133, v160, v122
	v_add_f32_e32 v131, v133, v131
	v_mul_f32_e32 v133, v158, v121
	v_add_f32_e32 v131, v133, v131
	v_mul_f32_e32 v133, v159, v120
	v_add_f32_e32 v131, v131, v133
	v_mul_f32_e32 v132, 0xbfb8aa3b, v131
	v_exp_f32_e32 v132, v132
	v_add_f32_e32 v108, 1.0, v108
	v_rcp_f32_e32 v108, v108
	v_mul_f32_e32 v102, v102, v106
	v_cvt_pk_bf16_f32 v102, v102, v102
	ds_write_b16 v112, v102 offset:22176
	s_waitcnt lgkmcnt(0)
; __device__ __forceinline__ float bf2f(u16 h) { return __uint_as_float(((uint32_t)h) << 16); }
; __device__ __forceinline__ float siluf(float x) { return x * __builtin_amdgcn_rcpf(1.f + __builtin_amdgcn_exp2f(x * -1.4426950408889634f)); }
; __device__ __forceinline__ void ssd_phase(const Params& p, int j, char* smem) {
;     ...
;         const float nh2 = bf2f(colp[(CL - 1) * cld]), nh1 = bf2f(colp[(CL - 2) * cld]), nh0 = bf2f(colp[(CL - 3) * cld]);
;         float a = bf2f(colp[63 * cld]), b1 = bf2f(colp[62 * cld]), c1 = bf2f(colp[61 * cld]);
; #pragma unroll 8
;         for (int s = 63; s >= 3; --s) {
;           const float d = bf2f(colp[(s - 3) * cld]);
;           float o = siluf(cbias + cw3 * a + cw2 * b1 + cw1 * c1 + cw0 * d);
;           if (s >= CL) o = 0.f;
;           colp[s * cld] = f2bf(o);
;           a = b1; b1 = c1; c1 = d;
;         }
	v_lshlrev_b32_e32 v119, 16, v119
	v_lshlrev_b32_e32 v118, 16, v118
	v_lshlrev_b32_e32 v117, 16, v117
	v_lshlrev_b32_e32 v116, 16, v116
	v_lshlrev_b32_e32 v115, 16, v115
	v_lshlrev_b32_e32 v130, 16, v130
	v_lshlrev_b32_e32 v129, 16, v129
	v_lshlrev_b32_e32 v128, 16, v128
	v_mul_f32_e32 v133, v161, v122
	v_add_f32_e32 v102, v153, v133
	v_mul_f32_e32 v133, v160, v121
	v_add_f32_e32 v102, v133, v102
	v_mul_f32_e32 v133, v158, v120
	v_add_f32_e32 v102, v133, v102
	v_mul_f32_e32 v133, v159, v119
	v_add_f32_e32 v102, v102, v133
	v_mul_f32_e32 v106, 0xbfb8aa3b, v102
	v_exp_f32_e32 v106, v106
	v_add_f32_e32 v132, 1.0, v132
	v_rcp_f32_e32 v132, v132
	v_mul_f32_e32 v107, v107, v108
	v_cvt_pk_bf16_f32 v107, v107, v107
	ds_write_b16 v112, v107 offset:21648
	v_mul_f32_e32 v133, v161, v121
	v_add_f32_e32 v107, v153, v133
	v_mul_f32_e32 v133, v160, v120
	v_add_f32_e32 v107, v133, v107
	v_mul_f32_e32 v133, v158, v119
	v_add_f32_e32 v107, v133, v107
	v_mul_f32_e32 v133, v159, v118
	v_add_f32_e32 v107, v107, v133
	v_mul_f32_e32 v108, 0xbfb8aa3b, v107
	v_exp_f32_e32 v108, v108
	v_add_f32_e32 v106, 1.0, v106
	v_rcp_f32_e32 v106, v106
	v_mul_f32_e32 v131, v131, v132
	v_cvt_pk_bf16_f32 v131, v131, v131
	ds_write_b16 v112, v131 offset:21120
	v_mul_f32_e32 v133, v161, v120
	v_add_f32_e32 v131, v153, v133
	v_mul_f32_e32 v133, v160, v119
	v_add_f32_e32 v131, v133, v131
	v_mul_f32_e32 v133, v158, v118
	v_add_f32_e32 v131, v133, v131
	v_mul_f32_e32 v133, v159, v117
	v_add_f32_e32 v131, v131, v133
	v_mul_f32_e32 v132, 0xbfb8aa3b, v131
	v_exp_f32_e32 v132, v132
	v_add_f32_e32 v108, 1.0, v108
	v_rcp_f32_e32 v108, v108
	v_mul_f32_e32 v102, v102, v106
	v_cvt_pk_bf16_f32 v102, v102, v102
	ds_write_b16 v112, v102 offset:20592
	v_mul_f32_e32 v133, v161, v119
	v_add_f32_e32 v102, v153, v133
	v_mul_f32_e32 v133, v160, v118
	v_add_f32_e32 v102, v133, v102
	v_mul_f32_e32 v133, v158, v117
	v_add_f32_e32 v102, v133, v102
	v_mul_f32_e32 v133, v159, v116
	v_add_f32_e32 v102, v102, v133
	v_mul_f32_e32 v106, 0xbfb8aa3b, v102
	v_exp_f32_e32 v106, v106
	v_add_f32_e32 v132, 1.0, v132
	v_rcp_f32_e32 v132, v132
	v_mul_f32_e32 v107, v107, v108
	v_cvt_pk_bf16_f32 v107, v107, v107
	ds_write_b16 v112, v107 offset:20064
	ds_read_u16 v127, v112 offset:14784
	ds_read_u16 v126, v112 offset:14256
	ds_read_u16 v125, v112 offset:13728
	ds_read_u16 v124, v112 offset:13200
	ds_read_u16 v123, v112 offset:12672
	ds_read_u16 v122, v112 offset:12144
	ds_read_u16 v121, v112 offset:11616
	ds_read_u16 v120, v112 offset:11088
	v_mul_f32_e32 v133, v161, v118
	v_add_f32_e32 v107, v153, v133
	v_mul_f32_e32 v133, v160, v117
	v_add_f32_e32 v107, v133, v107
	v_mul_f32_e32 v133, v158, v116
	v_add_f32_e32 v107, v133, v107
	v_mul_f32_e32 v133, v159, v115
	v_add_f32_e32 v107, v107, v133
	v_mul_f32_e32 v108, 0xbfb8aa3b, v107
	v_exp_f32_e32 v108, v108
	v_add_f32_e32 v106, 1.0, v106
	v_rcp_f32_e32 v106, v106
	v_mul_f32_e32 v131, v131, v132
	v_cvt_pk_bf16_f32 v131, v131, v131
	ds_write_b16 v112, v131 offset:19536
	v_mul_f32_e32 v133, v161, v117
	v_add_f32_e32 v131, v153, v133
	v_mul_f32_e32 v133, v160, v116
	v_add_f32_e32 v131, v133, v131
	v_mul_f32_e32 v133, v158, v115
	v_add_f32_e32 v131, v133, v131
	v_mul_f32_e32 v133, v159, v130
	v_add_f32_e32 v131, v131, v133
	v_mul_f32_e32 v132, 0xbfb8aa3b, v131
	v_exp_f32_e32 v132, v132
	v_add_f32_e32 v108, 1.0, v108
	v_rcp_f32_e32 v108, v108
	v_mul_f32_e32 v102, v102, v106
	v_cvt_pk_bf16_f32 v102, v102, v102
	ds_write_b16 v112, v102 offset:19008
	v_mul_f32_e32 v133, v161, v116
	v_add_f32_e32 v102, v153, v133
	v_mul_f32_e32 v133, v160, v115
	v_add_f32_e32 v102, v133, v102
	v_mul_f32_e32 v133, v158, v130
	v_add_f32_e32 v102, v133, v102
	v_mul_f32_e32 v133, v159, v129
	v_add_f32_e32 v102, v102, v133
	v_mul_f32_e32 v106, 0xbfb8aa3b, v102
	v_exp_f32_e32 v106, v106
	v_add_f32_e32 v132, 1.0, v132
	v_rcp_f32_e32 v132, v132
	v_mul_f32_e32 v107, v107, v108
	v_cvt_pk_bf16_f32 v107, v107, v107
	ds_write_b16 v112, v107 offset:18480
	v_mul_f32_e32 v133, v161, v115
	v_add_f32_e32 v107, v153, v133
	v_mul_f32_e32 v133, v160, v130
	v_add_f32_e32 v107, v133, v107
	v_mul_f32_e32 v133, v158, v129
	v_add_f32_e32 v107, v133, v107
	v_mul_f32_e32 v133, v159, v128
	v_add_f32_e32 v107, v107, v133
	v_mul_f32_e32 v108, 0xbfb8aa3b, v107
	v_exp_f32_e32 v108, v108
	v_add_f32_e32 v106, 1.0, v106
	v_rcp_f32_e32 v106, v106
	v_mul_f32_e32 v131, v131, v132
	v_cvt_pk_bf16_f32 v131, v131, v131
	ds_write_b16 v112, v131 offset:17952
	s_waitcnt lgkmcnt(0)
; __device__ __forceinline__ float bf2f(u16 h) { return __uint_as_float(((uint32_t)h) << 16); }
; __device__ __forceinline__ float siluf(float x) { return x * __builtin_amdgcn_rcpf(1.f + __builtin_amdgcn_exp2f(x * -1.4426950408889634f)); }
; __device__ __forceinline__ void ssd_phase(const Params& p, int j, char* smem) {
;     ...
;         const float nh2 = bf2f(colp[(CL - 1) * cld]), nh1 = bf2f(colp[(CL - 2) * cld]), nh0 = bf2f(colp[(CL - 3) * cld]);
;         float a = bf2f(colp[63 * cld]), b1 = bf2f(colp[62 * cld]), c1 = bf2f(colp[61 * cld]);
; #pragma unroll 8
;         for (int s = 63; s >= 3; --s) {
;           const float d = bf2f(colp[(s - 3) * cld]);
;           float o = siluf(cbias + cw3 * a + cw2 * b1 + cw1 * c1 + cw0 * d);
;           if (s >= CL) o = 0.f;
;           colp[s * cld] = f2bf(o);
;           a = b1; b1 = c1; c1 = d;
;         }
	v_lshlrev_b32_e32 v127, 16, v127
	v_lshlrev_b32_e32 v126, 16, v126
	v_lshlrev_b32_e32 v125, 16, v125
	v_lshlrev_b32_e32 v124, 16, v124
	v_lshlrev_b32_e32 v123, 16, v123
	v_lshlrev_b32_e32 v122, 16, v122
	v_lshlrev_b32_e32 v121, 16, v121
	v_lshlrev_b32_e32 v120, 16, v120
	v_mul_f32_e32 v133, v161, v130
	v_add_f32_e32 v131, v153, v133
	v_mul_f32_e32 v133, v160, v129
	v_add_f32_e32 v131, v133, v131
	v_mul_f32_e32 v133, v158, v128
	v_add_f32_e32 v131, v133, v131
	v_mul_f32_e32 v133, v159, v127
	v_add_f32_e32 v131, v131, v133
	v_mul_f32_e32 v132, 0xbfb8aa3b, v131
	v_exp_f32_e32 v132, v132
	v_add_f32_e32 v108, 1.0, v108
	v_rcp_f32_e32 v108, v108
	v_mul_f32_e32 v102, v102, v106
	v_cvt_pk_bf16_f32 v102, v102, v102
	ds_write_b16 v112, v102 offset:17424
	v_mul_f32_e32 v133, v161, v129
	v_add_f32_e32 v102, v153, v133
	v_mul_f32_e32 v133, v160, v128
	v_add_f32_e32 v102, v133, v102
	v_mul_f32_e32 v133, v158, v127
	v_add_f32_e32 v102, v133, v102
	v_mul_f32_e32 v133, v159, v126
	v_add_f32_e32 v102, v102, v133
	v_mul_f32_e32 v106, 0xbfb8aa3b, v102
	v_exp_f32_e32 v106, v106
	v_add_f32_e32 v132, 1.0, v132
	v_rcp_f32_e32 v132, v132
	v_mul_f32_e32 v107, v107, v108
	v_cvt_pk_bf16_f32 v107, v107, v107
	ds_write_b16 v112, v107 offset:16896
	v_mul_f32_e32 v133, v161, v128
	v_add_f32_e32 v107, v153, v133
	v_mul_f32_e32 v133, v160, v127
	v_add_f32_e32 v107, v133, v107
	v_mul_f32_e32 v133, v158, v126
	v_add_f32_e32 v107, v133, v107
	v_mul_f32_e32 v133, v159, v125
	v_add_f32_e32 v107, v107, v133
	v_mul_f32_e32 v108, 0xbfb8aa3b, v107
	v_exp_f32_e32 v108, v108
	v_add_f32_e32 v106, 1.0, v106
	v_rcp_f32_e32 v106, v106
	v_mul_f32_e32 v131, v131, v132
	v_cvt_pk_bf16_f32 v131, v131, v131
	ds_write_b16 v112, v131 offset:16368
	v_mul_f32_e32 v133, v161, v127
	v_add_f32_e32 v131, v153, v133
	v_mul_f32_e32 v133, v160, v126
	v_add_f32_e32 v131, v133, v131
	v_mul_f32_e32 v133, v158, v125
	v_add_f32_e32 v131, v133, v131
	v_mul_f32_e32 v133, v159, v124
	v_add_f32_e32 v131, v131, v133
	v_mul_f32_e32 v132, 0xbfb8aa3b, v131
	v_exp_f32_e32 v132, v132
	v_add_f32_e32 v108, 1.0, v108
	v_rcp_f32_e32 v108, v108
	v_mul_f32_e32 v102, v102, v106
	v_cvt_pk_bf16_f32 v102, v102, v102
	ds_write_b16 v112, v102 offset:15840
	ds_read_u16 v119, v112 offset:10560
	ds_read_u16 v118, v112 offset:10032
	ds_read_u16 v117, v112 offset:9504
	ds_read_u16 v116, v112 offset:8976
	ds_read_u16 v115, v112 offset:8448
	ds_read_u16 v130, v112 offset:7920
	ds_read_u16 v129, v112 offset:7392
	ds_read_u16 v128, v112 offset:6864
	v_mul_f32_e32 v133, v161, v126
	v_add_f32_e32 v102, v153, v133
	v_mul_f32_e32 v133, v160, v125
	v_add_f32_e32 v102, v133, v102
	v_mul_f32_e32 v133, v158, v124
	v_add_f32_e32 v102, v133, v102
	v_mul_f32_e32 v133, v159, v123
	v_add_f32_e32 v102, v102, v133
	v_mul_f32_e32 v106, 0xbfb8aa3b, v102
	v_exp_f32_e32 v106, v106
	v_add_f32_e32 v132, 1.0, v132
	v_rcp_f32_e32 v132, v132
	v_mul_f32_e32 v107, v107, v108
	v_cvt_pk_bf16_f32 v107, v107, v107
	ds_write_b16 v112, v107 offset:15312
	v_mul_f32_e32 v133, v161, v125
	v_add_f32_e32 v107, v153, v133
	v_mul_f32_e32 v133, v160, v124
	v_add_f32_e32 v107, v133, v107
	v_mul_f32_e32 v133, v158, v123
	v_add_f32_e32 v107, v133, v107
	v_mul_f32_e32 v133, v159, v122
	v_add_f32_e32 v107, v107, v133
	v_mul_f32_e32 v108, 0xbfb8aa3b, v107
	v_exp_f32_e32 v108, v108
	v_add_f32_e32 v106, 1.0, v106
	v_rcp_f32_e32 v106, v106
	v_mul_f32_e32 v131, v131, v132
	v_cvt_pk_bf16_f32 v131, v131, v131
	ds_write_b16 v112, v131 offset:14784
	v_mul_f32_e32 v133, v161, v124
	v_add_f32_e32 v131, v153, v133
	v_mul_f32_e32 v133, v160, v123
	v_add_f32_e32 v131, v133, v131
	v_mul_f32_e32 v133, v158, v122
	v_add_f32_e32 v131, v133, v131
	v_mul_f32_e32 v133, v159, v121
	v_add_f32_e32 v131, v131, v133
	v_mul_f32_e32 v132, 0xbfb8aa3b, v131
	v_exp_f32_e32 v132, v132
	v_add_f32_e32 v108, 1.0, v108
	v_rcp_f32_e32 v108, v108
	v_mul_f32_e32 v102, v102, v106
	v_cvt_pk_bf16_f32 v102, v102, v102
	ds_write_b16 v112, v102 offset:14256
	v_mul_f32_e32 v133, v161, v123
	v_add_f32_e32 v102, v153, v133
	v_mul_f32_e32 v133, v160, v122
	v_add_f32_e32 v102, v133, v102
	v_mul_f32_e32 v133, v158, v121
	v_add_f32_e32 v102, v133, v102
	v_mul_f32_e32 v133, v159, v120
	v_add_f32_e32 v102, v102, v133
	v_mul_f32_e32 v106, 0xbfb8aa3b, v102
	v_exp_f32_e32 v106, v106
	v_add_f32_e32 v132, 1.0, v132
	v_rcp_f32_e32 v132, v132
	v_mul_f32_e32 v107, v107, v108
	v_cvt_pk_bf16_f32 v107, v107, v107
	ds_write_b16 v112, v107 offset:13728
	s_waitcnt lgkmcnt(0)
; __device__ __forceinline__ float bf2f(u16 h) { return __uint_as_float(((uint32_t)h) << 16); }
; __device__ __forceinline__ float siluf(float x) { return x * __builtin_amdgcn_rcpf(1.f + __builtin_amdgcn_exp2f(x * -1.4426950408889634f)); }
; __device__ __forceinline__ void ssd_phase(const Params& p, int j, char* smem) {
;     ...
;         const float nh2 = bf2f(colp[(CL - 1) * cld]), nh1 = bf2f(colp[(CL - 2) * cld]), nh0 = bf2f(colp[(CL - 3) * cld]);
;         float a = bf2f(colp[63 * cld]), b1 = bf2f(colp[62 * cld]), c1 = bf2f(colp[61 * cld]);
; #pragma unroll 8
;         for (int s = 63; s >= 3; --s) {
;           const float d = bf2f(colp[(s - 3) * cld]);
;           float o = siluf(cbias + cw3 * a + cw2 * b1 + cw1 * c1 + cw0 * d);
;           if (s >= CL) o = 0.f;
;           colp[s * cld] = f2bf(o);
;           a = b1; b1 = c1; c1 = d;
;         }
	v_lshlrev_b32_e32 v119, 16, v119
	v_lshlrev_b32_e32 v118, 16, v118
	v_lshlrev_b32_e32 v117, 16, v117
	v_lshlrev_b32_e32 v116, 16, v116
	v_lshlrev_b32_e32 v115, 16, v115
	v_lshlrev_b32_e32 v130, 16, v130
	v_lshlrev_b32_e32 v129, 16, v129
	v_lshlrev_b32_e32 v128, 16, v128
	v_mul_f32_e32 v133, v161, v122
	v_add_f32_e32 v107, v153, v133
	v_mul_f32_e32 v133, v160, v121
	v_add_f32_e32 v107, v133, v107
	v_mul_f32_e32 v133, v158, v120
	v_add_f32_e32 v107, v133, v107
	v_mul_f32_e32 v133, v159, v119
	v_add_f32_e32 v107, v107, v133
	v_mul_f32_e32 v108, 0xbfb8aa3b, v107
	v_exp_f32_e32 v108, v108
	v_add_f32_e32 v106, 1.0, v106
	v_rcp_f32_e32 v106, v106
	v_mul_f32_e32 v131, v131, v132
	v_cvt_pk_bf16_f32 v131, v131, v131
	ds_write_b16 v112, v131 offset:13200
	v_mul_f32_e32 v133, v161, v121
	v_add_f32_e32 v131, v153, v133
	v_mul_f32_e32 v133, v160, v120
	v_add_f32_e32 v131, v133, v131
	v_mul_f32_e32 v133, v158, v119
	v_add_f32_e32 v131, v133, v131
	v_mul_f32_e32 v133, v159, v118
	v_add_f32_e32 v131, v131, v133
	v_mul_f32_e32 v132, 0xbfb8aa3b, v131
	v_exp_f32_e32 v132, v132
	v_add_f32_e32 v108, 1.0, v108
	v_rcp_f32_e32 v108, v108
	v_mul_f32_e32 v102, v102, v106
	v_cvt_pk_bf16_f32 v102, v102, v102
	ds_write_b16 v112, v102 offset:12672
	v_mul_f32_e32 v133, v161, v120
	v_add_f32_e32 v102, v153, v133
	v_mul_f32_e32 v133, v160, v119
	v_add_f32_e32 v102, v133, v102
	v_mul_f32_e32 v133, v158, v118
	v_add_f32_e32 v102, v133, v102
	v_mul_f32_e32 v133, v159, v117
	v_add_f32_e32 v102, v102, v133
	v_mul_f32_e32 v106, 0xbfb8aa3b, v102
	v_exp_f32_e32 v106, v106
	v_add_f32_e32 v132, 1.0, v132
	v_rcp_f32_e32 v132, v132
	v_mul_f32_e32 v107, v107, v108
	v_cvt_pk_bf16_f32 v107, v107, v107
	ds_write_b16 v112, v107 offset:12144
	v_mul_f32_e32 v133, v161, v119
	v_add_f32_e32 v107, v153, v133
	v_mul_f32_e32 v133, v160, v118
	v_add_f32_e32 v107, v133, v107
	v_mul_f32_e32 v133, v158, v117
	v_add_f32_e32 v107, v133, v107
	v_mul_f32_e32 v133, v159, v116
	v_add_f32_e32 v107, v107, v133
	v_mul_f32_e32 v108, 0xbfb8aa3b, v107
	v_exp_f32_e32 v108, v108
	v_add_f32_e32 v106, 1.0, v106
	v_rcp_f32_e32 v106, v106
	v_mul_f32_e32 v131, v131, v132
	v_cvt_pk_bf16_f32 v131, v131, v131
	ds_write_b16 v112, v131 offset:11616
	ds_read_u16 v127, v112 offset:6336
	ds_read_u16 v126, v112 offset:5808
	ds_read_u16 v125, v112 offset:5280
	ds_read_u16 v124, v112 offset:4752
	ds_read_u16 v123, v112 offset:4224
	ds_read_u16 v122, v112 offset:3696
	ds_read_u16 v121, v112 offset:3168
	ds_read_u16 v120, v112 offset:2640
	v_mul_f32_e32 v133, v161, v118
	v_add_f32_e32 v131, v153, v133
	v_mul_f32_e32 v133, v160, v117
	v_add_f32_e32 v131, v133, v131
	v_mul_f32_e32 v133, v158, v116
	v_add_f32_e32 v131, v133, v131
	v_mul_f32_e32 v133, v159, v115
	v_add_f32_e32 v131, v131, v133
	v_mul_f32_e32 v132, 0xbfb8aa3b, v131
	v_exp_f32_e32 v132, v132
	v_add_f32_e32 v108, 1.0, v108
	v_rcp_f32_e32 v108, v108
	v_mul_f32_e32 v102, v102, v106
	v_cvt_pk_bf16_f32 v102, v102, v102
	ds_write_b16 v112, v102 offset:11088
	v_mul_f32_e32 v133, v161, v117
	v_add_f32_e32 v102, v153, v133
	v_mul_f32_e32 v133, v160, v116
	v_add_f32_e32 v102, v133, v102
	v_mul_f32_e32 v133, v158, v115
	v_add_f32_e32 v102, v133, v102
	v_mul_f32_e32 v133, v159, v130
	v_add_f32_e32 v102, v102, v133
	v_mul_f32_e32 v106, 0xbfb8aa3b, v102
	v_exp_f32_e32 v106, v106
	v_add_f32_e32 v132, 1.0, v132
	v_rcp_f32_e32 v132, v132
	v_mul_f32_e32 v107, v107, v108
	v_cvt_pk_bf16_f32 v107, v107, v107
	ds_write_b16 v112, v107 offset:10560
	v_mul_f32_e32 v133, v161, v116
	v_add_f32_e32 v107, v153, v133
	v_mul_f32_e32 v133, v160, v115
	v_add_f32_e32 v107, v133, v107
	v_mul_f32_e32 v133, v158, v130
	v_add_f32_e32 v107, v133, v107
	v_mul_f32_e32 v133, v159, v129
	v_add_f32_e32 v107, v107, v133
	v_mul_f32_e32 v108, 0xbfb8aa3b, v107
	v_exp_f32_e32 v108, v108
	v_add_f32_e32 v106, 1.0, v106
	v_rcp_f32_e32 v106, v106
	v_mul_f32_e32 v131, v131, v132
	v_cvt_pk_bf16_f32 v131, v131, v131
	ds_write_b16 v112, v131 offset:10032
	v_mul_f32_e32 v133, v161, v115
	v_add_f32_e32 v131, v153, v133
	v_mul_f32_e32 v133, v160, v130
	v_add_f32_e32 v131, v133, v131
	v_mul_f32_e32 v133, v158, v129
	v_add_f32_e32 v131, v133, v131
	v_mul_f32_e32 v133, v159, v128
	v_add_f32_e32 v131, v131, v133
	v_mul_f32_e32 v132, 0xbfb8aa3b, v131
	v_exp_f32_e32 v132, v132
	v_add_f32_e32 v108, 1.0, v108
	v_rcp_f32_e32 v108, v108
	v_mul_f32_e32 v102, v102, v106
	v_cvt_pk_bf16_f32 v102, v102, v102
	ds_write_b16 v112, v102 offset:9504
	s_waitcnt lgkmcnt(0)
; __device__ __forceinline__ float bf2f(u16 h) { return __uint_as_float(((uint32_t)h) << 16); }
; __device__ __forceinline__ float siluf(float x) { return x * __builtin_amdgcn_rcpf(1.f + __builtin_amdgcn_exp2f(x * -1.4426950408889634f)); }
; __device__ __forceinline__ void ssd_phase(const Params& p, int j, char* smem) {
;     ...
;         const float nh2 = bf2f(colp[(CL - 1) * cld]), nh1 = bf2f(colp[(CL - 2) * cld]), nh0 = bf2f(colp[(CL - 3) * cld]);
;         float a = bf2f(colp[63 * cld]), b1 = bf2f(colp[62 * cld]), c1 = bf2f(colp[61 * cld]);
; #pragma unroll 8
;         for (int s = 63; s >= 3; --s) {
;           const float d = bf2f(colp[(s - 3) * cld]);
;           float o = siluf(cbias + cw3 * a + cw2 * b1 + cw1 * c1 + cw0 * d);
;           if (s >= CL) o = 0.f;
;           colp[s * cld] = f2bf(o);
;           a = b1; b1 = c1; c1 = d;
;         }
	v_lshlrev_b32_e32 v127, 16, v127
	v_lshlrev_b32_e32 v126, 16, v126
	v_lshlrev_b32_e32 v125, 16, v125
	v_lshlrev_b32_e32 v124, 16, v124
	v_lshlrev_b32_e32 v123, 16, v123
	v_lshlrev_b32_e32 v122, 16, v122
	v_lshlrev_b32_e32 v121, 16, v121
	v_lshlrev_b32_e32 v120, 16, v120
	v_mul_f32_e32 v133, v161, v130
	v_add_f32_e32 v102, v153, v133
	v_mul_f32_e32 v133, v160, v129
	v_add_f32_e32 v102, v133, v102
	v_mul_f32_e32 v133, v158, v128
	v_add_f32_e32 v102, v133, v102
	v_mul_f32_e32 v133, v159, v127
	v_add_f32_e32 v102, v102, v133
	v_mul_f32_e32 v106, 0xbfb8aa3b, v102
	v_exp_f32_e32 v106, v106
	v_add_f32_e32 v132, 1.0, v132
	v_rcp_f32_e32 v132, v132
	v_mul_f32_e32 v107, v107, v108
	v_cvt_pk_bf16_f32 v107, v107, v107
	ds_write_b16 v112, v107 offset:8976
	v_mul_f32_e32 v133, v161, v129
	v_add_f32_e32 v107, v153, v133
	v_mul_f32_e32 v133, v160, v128
	v_add_f32_e32 v107, v133, v107
	v_mul_f32_e32 v133, v158, v127
	v_add_f32_e32 v107, v133, v107
	v_mul_f32_e32 v133, v159, v126
	v_add_f32_e32 v107, v107, v133
	v_mul_f32_e32 v108, 0xbfb8aa3b, v107
	v_exp_f32_e32 v108, v108
	v_add_f32_e32 v106, 1.0, v106
	v_rcp_f32_e32 v106, v106
	v_mul_f32_e32 v131, v131, v132
	v_cvt_pk_bf16_f32 v131, v131, v131
	ds_write_b16 v112, v131 offset:8448
	v_mul_f32_e32 v133, v161, v128
	v_add_f32_e32 v131, v153, v133
	v_mul_f32_e32 v133, v160, v127
	v_add_f32_e32 v131, v133, v131
	v_mul_f32_e32 v133, v158, v126
	v_add_f32_e32 v131, v133, v131
	v_mul_f32_e32 v133, v159, v125
	v_add_f32_e32 v131, v131, v133
	v_mul_f32_e32 v132, 0xbfb8aa3b, v131
	v_exp_f32_e32 v132, v132
	v_add_f32_e32 v108, 1.0, v108
	v_rcp_f32_e32 v108, v108
	v_mul_f32_e32 v102, v102, v106
	v_cvt_pk_bf16_f32 v102, v102, v102
	ds_write_b16 v112, v102 offset:7920
	v_mul_f32_e32 v133, v161, v127
	v_add_f32_e32 v102, v153, v133
	v_mul_f32_e32 v133, v160, v126
	v_add_f32_e32 v102, v133, v102
	v_mul_f32_e32 v133, v158, v125
	v_add_f32_e32 v102, v133, v102
	v_mul_f32_e32 v133, v159, v124
	v_add_f32_e32 v102, v102, v133
	v_mul_f32_e32 v106, 0xbfb8aa3b, v102
	v_exp_f32_e32 v106, v106
	v_add_f32_e32 v132, 1.0, v132
	v_rcp_f32_e32 v132, v132
	v_mul_f32_e32 v107, v107, v108
	v_cvt_pk_bf16_f32 v107, v107, v107
	ds_write_b16 v112, v107 offset:7392
	ds_read_u16 v119, v112 offset:2112
	ds_read_u16 v118, v112 offset:1584
	ds_read_u16 v117, v112 offset:1056
	ds_read_u16 v116, v112 offset:528
	ds_read_u16 v115, v112 offset:0
	v_mul_f32_e32 v133, v161, v126
	v_add_f32_e32 v107, v153, v133
	v_mul_f32_e32 v133, v160, v125
	v_add_f32_e32 v107, v133, v107
	v_mul_f32_e32 v133, v158, v124
	v_add_f32_e32 v107, v133, v107
	v_mul_f32_e32 v133, v159, v123
	v_add_f32_e32 v107, v107, v133
	v_mul_f32_e32 v108, 0xbfb8aa3b, v107
	v_exp_f32_e32 v108, v108
	v_add_f32_e32 v106, 1.0, v106
	v_rcp_f32_e32 v106, v106
	v_mul_f32_e32 v131, v131, v132
	v_cvt_pk_bf16_f32 v131, v131, v131
	ds_write_b16 v112, v131 offset:6864
	v_mul_f32_e32 v133, v161, v125
	v_add_f32_e32 v131, v153, v133
	v_mul_f32_e32 v133, v160, v124
	v_add_f32_e32 v131, v133, v131
	v_mul_f32_e32 v133, v158, v123
	v_add_f32_e32 v131, v133, v131
	v_mul_f32_e32 v133, v159, v122
	v_add_f32_e32 v131, v131, v133
	v_mul_f32_e32 v132, 0xbfb8aa3b, v131
	v_exp_f32_e32 v132, v132
	v_add_f32_e32 v108, 1.0, v108
	v_rcp_f32_e32 v108, v108
	v_mul_f32_e32 v102, v102, v106
	v_cvt_pk_bf16_f32 v102, v102, v102
	ds_write_b16 v112, v102 offset:6336
	v_mul_f32_e32 v133, v161, v124
	v_add_f32_e32 v102, v153, v133
	v_mul_f32_e32 v133, v160, v123
	v_add_f32_e32 v102, v133, v102
	v_mul_f32_e32 v133, v158, v122
	v_add_f32_e32 v102, v133, v102
	v_mul_f32_e32 v133, v159, v121
	v_add_f32_e32 v102, v102, v133
	v_mul_f32_e32 v106, 0xbfb8aa3b, v102
	v_exp_f32_e32 v106, v106
	v_add_f32_e32 v132, 1.0, v132
	v_rcp_f32_e32 v132, v132
	v_mul_f32_e32 v107, v107, v108
	v_cvt_pk_bf16_f32 v107, v107, v107
	ds_write_b16 v112, v107 offset:5808
	v_mul_f32_e32 v133, v161, v123
	v_add_f32_e32 v107, v153, v133
	v_mul_f32_e32 v133, v160, v122
	v_add_f32_e32 v107, v133, v107
	v_mul_f32_e32 v133, v158, v121
	v_add_f32_e32 v107, v133, v107
	v_mul_f32_e32 v133, v159, v120
	v_add_f32_e32 v107, v107, v133
	v_mul_f32_e32 v108, 0xbfb8aa3b, v107
	v_exp_f32_e32 v108, v108
	v_add_f32_e32 v106, 1.0, v106
	v_rcp_f32_e32 v106, v106
	v_mul_f32_e32 v131, v131, v132
	v_cvt_pk_bf16_f32 v131, v131, v131
	ds_write_b16 v112, v131 offset:5280
	s_waitcnt lgkmcnt(0)
; __device__ __forceinline__ float bf2f(u16 h) { return __uint_as_float(((uint32_t)h) << 16); }
; __device__ __forceinline__ float siluf(float x) { return x * __builtin_amdgcn_rcpf(1.f + __builtin_amdgcn_exp2f(x * -1.4426950408889634f)); }
; __device__ __forceinline__ void ssd_phase(const Params& p, int j, char* smem) {
;     ...
;         for (int s = 63; s >= 3; --s) {
;           const float d = bf2f(colp[(s - 3) * cld]);
;           float o = siluf(cbias + cw3 * a + cw2 * b1 + cw1 * c1 + cw0 * d);
;           if (s >= CL) o = 0.f;
;           colp[s * cld] = f2bf(o);
;           a = b1; b1 = c1; c1 = d;
;         }
;         colp[2 * cld] = f2bf(siluf(cbias + cw3 * a + cw2 * b1 + cw1 * c1 + cw0 * hl2));
;         colp[1 * cld] = f2bf(siluf(cbias + cw3 * b1 + cw2 * c1 + cw1 * hl2 + cw0 * hl1));
;         colp[0] = f2bf(siluf(cbias + cw3 * c1 + cw2 * hl2 + cw1 * hl1 + cw0 * hl0));
;         hl0 = nh0; hl1 = nh1; hl2 = nh2;
	v_lshlrev_b32_e32 v119, 16, v119
	v_lshlrev_b32_e32 v118, 16, v118
	v_lshlrev_b32_e32 v117, 16, v117
	v_lshlrev_b32_e32 v116, 16, v116
	v_lshlrev_b32_e32 v115, 16, v115
	v_mul_f32_e32 v133, v161, v122
	v_add_f32_e32 v131, v153, v133
	v_mul_f32_e32 v133, v160, v121
	v_add_f32_e32 v131, v133, v131
	v_mul_f32_e32 v133, v158, v120
	v_add_f32_e32 v131, v133, v131
	v_mul_f32_e32 v133, v159, v119
	v_add_f32_e32 v131, v131, v133
	v_mul_f32_e32 v132, 0xbfb8aa3b, v131
	v_exp_f32_e32 v132, v132
	v_add_f32_e32 v108, 1.0, v108
	v_rcp_f32_e32 v108, v108
	v_mul_f32_e32 v102, v102, v106
	v_cvt_pk_bf16_f32 v102, v102, v102
	ds_write_b16 v112, v102 offset:4752
	v_mul_f32_e32 v133, v161, v121
	v_add_f32_e32 v102, v153, v133
	v_mul_f32_e32 v133, v160, v120
	v_add_f32_e32 v102, v133, v102
	v_mul_f32_e32 v133, v158, v119
	v_add_f32_e32 v102, v133, v102
	v_mul_f32_e32 v133, v159, v118
	v_add_f32_e32 v102, v102, v133
	v_mul_f32_e32 v106, 0xbfb8aa3b, v102
	v_exp_f32_e32 v106, v106
	v_add_f32_e32 v132, 1.0, v132
	v_rcp_f32_e32 v132, v132
	v_mul_f32_e32 v107, v107, v108
	v_cvt_pk_bf16_f32 v107, v107, v107
	ds_write_b16 v112, v107 offset:4224
	v_mul_f32_e32 v133, v161, v120
	v_add_f32_e32 v107, v153, v133
	v_mul_f32_e32 v133, v160, v119
	v_add_f32_e32 v107, v133, v107
	v_mul_f32_e32 v133, v158, v118
	v_add_f32_e32 v107, v133, v107
	v_mul_f32_e32 v133, v159, v117
	v_add_f32_e32 v107, v107, v133
	v_mul_f32_e32 v108, 0xbfb8aa3b, v107
	v_exp_f32_e32 v108, v108
	v_add_f32_e32 v106, 1.0, v106
	v_rcp_f32_e32 v106, v106
	v_mul_f32_e32 v131, v131, v132
	v_cvt_pk_bf16_f32 v131, v131, v131
	ds_write_b16 v112, v131 offset:3696
	v_mul_f32_e32 v133, v161, v119
	v_add_f32_e32 v131, v153, v133
	v_mul_f32_e32 v133, v160, v118
	v_add_f32_e32 v131, v133, v131
	v_mul_f32_e32 v133, v158, v117
	v_add_f32_e32 v131, v133, v131
	v_mul_f32_e32 v133, v159, v116
	v_add_f32_e32 v131, v131, v133
	v_mul_f32_e32 v132, 0xbfb8aa3b, v131
	v_exp_f32_e32 v132, v132
	v_add_f32_e32 v108, 1.0, v108
	v_rcp_f32_e32 v108, v108
	v_mul_f32_e32 v102, v102, v106
	v_cvt_pk_bf16_f32 v102, v102, v102
	ds_write_b16 v112, v102 offset:3168
	v_mul_f32_e32 v133, v161, v118
	v_add_f32_e32 v102, v153, v133
	v_mul_f32_e32 v133, v160, v117
	v_add_f32_e32 v102, v133, v102
	v_mul_f32_e32 v133, v158, v116
	v_add_f32_e32 v102, v133, v102
	v_mul_f32_e32 v133, v159, v115
	v_add_f32_e32 v102, v102, v133
	v_mul_f32_e32 v106, 0xbfb8aa3b, v102
	v_exp_f32_e32 v106, v106
	v_add_f32_e32 v132, 1.0, v132
	v_rcp_f32_e32 v132, v132
	v_mul_f32_e32 v107, v107, v108
	v_cvt_pk_bf16_f32 v107, v107, v107
	ds_write_b16 v112, v107 offset:2640
	v_add_f32_e32 v106, 1.0, v106
	v_rcp_f32_e32 v106, v106
	v_mul_f32_e32 v131, v131, v132
	v_cvt_pk_bf16_f32 v131, v131, v131
	ds_write_b16 v112, v131 offset:2112
	v_mul_f32_e32 v102, v102, v106
	v_cvt_pk_bf16_f32 v102, v102, v102
	ds_write_b16 v112, v102 offset:1584
	v_mov_b32_e32 v103, v117
	v_mov_b32_e32 v104, v116
	v_mov_b32_e32 v105, v115
	s_branch .LBB0_254
.Lmy_conv_orig:
	s_mov_b32 s0, 63
	s_branch .LBB0_252
